# LDS read pipelining tool applied also to sample-item and mc_item<0/1> MFMA blocks (on top of ma_ret pipelining)
# speedup vs baseline: 1.0010x; 1.0010x over previous
; __device__ __forceinline__ unsigned pk2(float lo, float hi) { return pg8::cvt_pk_bf16(lo, hi); }
; __device__ __forceinline__ f32x4 mma16(bf16x8 a, bf16x8 b, f32x4 c) { return __builtin_amdgcn_mfma_f32_16x16x32_bf16(a, b, c, 0, 0, 0); }
; #define BSYNC() do { asm volatile("s_waitcnt vmcnt(0) lgkmcnt(0)" ::: "memory"); __syncthreads(); } while (0)
; template <int TY> __device__ __forceinline__ void ma_even_item(const Params& p, ldsp lds, int item) {
;     ...
;     f32x4 acc[DK / 16];
; #pragma unroll
;     for (int i = 0; i < DK / 16; ++i) acc[i] = (f32x4){0.f, 0.f, 0.f, 0.f};
; #pragma unroll
;     for (int ks = 0; ks < 2; ++ks) { const bf16x8 bf = ldfrag(VT, (16 * wave + l15) * 72 + 32 * ks + 8 * q4);
; #pragma unroll
;         for (int i = 0; i < DK / 16; ++i) acc[i] = mma16(ldfrag(KHT, (16 * i + l15) * 72 + 32 * ks + 8 * q4), bf, acc[i]); }
;     bf16_t* HL = (bf16_t*)(p.ws + WS_HL + (TY ? HL_HGRN : 0)) + ((size_t)item * 128 + 16 * wave + l15) * DK;
; #pragma unroll
;     for (int i = 0; i < DK / 16; ++i) { u32x2 w; w.x = pk2(acc[i][0], acc[i][1]); w.y = pk2(acc[i][2], acc[i][3]); *(u32x2*)(HL + 16 * i + 4 * q4) = w; }
;     BSYNC();
.LBB0_1048:
	s_or_b64 exec, exec, s[0:1]
	v_and_b32_e32 v0, 63, v0
	s_lshl_b32 s0, s8, 4
	v_lshrrev_b32_e32 v0, 1, v0
	v_mov_b32_e32 v12, 0x480
	v_mov_b32_e32 v18, 0x900
	v_mov_b32_e32 v22, 0xd80
	v_or_b32_e32 v1, s0, v7
	v_and_b32_e32 v16, 24, v0
	v_mad_u32_u24 v30, v7, s53, v12
	v_mad_u32_u24 v31, v7, s53, v18
	v_mad_u32_u24 v32, v7, s53, v22
	v_mad_u64_u32 v[0:1], s[8:9], v1, s53, v[16:17]
	v_mad_u32_u24 v8, v7, s53, v16
	v_add_u32_e32 v12, v16, v30
	v_add_u32_e32 v18, v16, v31
	v_add_u32_e32 v22, v16, v32
	v_lshl_add_u32 v6, v0, 1, 0
	v_lshl_add_u32 v8, v8, 1, 0
	v_lshl_add_u32 v12, v12, 1, 0
	v_lshl_add_u32 v18, v18, 1, 0
	v_lshl_add_u32 v22, v22, 1, 0
	s_waitcnt vmcnt(0) lgkmcnt(0)
	s_nop 0
	s_barrier
	ds_read_b128 v[186:189], v6 offset:59392
	ds_read_b128 v[190:193], v8 offset:40960
	ds_read_b128 v[194:197], v12 offset:40960
	ds_read_b128 v[206:209], v18 offset:40960
	ds_read_b128 v[218:221], v22 offset:40960
	ds_read_b128 v[222:225], v6 offset:59456
	s_nop 5
	s_waitcnt lgkmcnt(4)
	v_mfma_f32_16x16x32_bf16 v[8:11], v[190:193], v[186:189], 0
	v_lshlrev_b64 v[4:5], 7, v[4:5]
	s_ashr_i32 s1, s0, 31
	v_lshl_add_u64 v[4:5], v[4:5], 0, s[0:1]
	s_nop 0
	s_waitcnt lgkmcnt(3)
	v_mfma_f32_16x16x32_bf16 v[12:15], v[194:197], v[186:189], 0
	v_or_b32_e32 v4, v4, v7
	v_readlane_b32 s0, v253, 34
	v_lshlrev_b64 v[4:5], 7, v[4:5]
	s_nop 0
	s_waitcnt lgkmcnt(2)
	v_mfma_f32_16x16x32_bf16 v[18:21], v[206:209], v[186:189], 0
	v_readlane_b32 s1, v253, 35
	s_nop 0
	s_waitcnt lgkmcnt(1)
	v_mfma_f32_16x16x32_bf16 v[0:3], v[218:221], v[186:189], 0
	s_nop 0
	v_or_b32_e32 v6, 32, v16
	v_mad_u32_u24 v26, v7, s53, v6
	v_lshl_add_u32 v26, v26, 1, 0
	ds_read_b128 v[186:189], v26 offset:40960
	s_nop 0
	v_lshl_add_u64 v[4:5], s[0:1], 0, v[4:5]
	s_nop 0
	s_waitcnt lgkmcnt(0)
	v_mfma_f32_16x16x32_bf16 v[8:11], v[186:189], v[222:225], v[8:11]
	v_add_u32_e32 v26, v6, v30
	v_lshl_add_u32 v26, v26, 1, 0
	ds_read_b128 v[186:189], v26 offset:40960
	s_nop 0
	v_lshl_add_u64 v[4:5], v[4:5], 0, v[16:17]
	s_nop 0
	s_waitcnt lgkmcnt(0)
	v_mfma_f32_16x16x32_bf16 v[12:15], v[186:189], v[222:225], v[12:15]
	v_add_u32_e32 v26, v6, v31
	v_lshl_add_u32 v26, v26, 1, 0
	ds_read_b128 v[186:189], v26 offset:40960
	s_nop 0
	v_add_u32_e32 v6, v6, v32
	v_lshl_add_u32 v6, v6, 1, 0
	ds_read_b128 v[190:193], v6 offset:40960
	s_nop 0
	s_waitcnt lgkmcnt(1)
	v_mfma_f32_16x16x32_bf16 v[18:21], v[186:189], v[222:225], v[18:21]
	s_nop 0
	v_cvt_pk_bf16_f32 v6, v8, v9
	v_cvt_pk_bf16_f32 v7, v10, v11
	s_nop 0
	s_waitcnt lgkmcnt(0)
	v_mfma_f32_16x16x32_bf16 v[0:3], v[190:193], v[222:225], v[0:3]
	global_store_dwordx2 v[4:5], v[6:7], off
	v_cvt_pk_bf16_f32 v6, v12, v13
	v_cvt_pk_bf16_f32 v7, v14, v15
	global_store_dwordx2 v[4:5], v[6:7], off offset:32
	v_cvt_pk_bf16_f32 v6, v18, v19
	v_cvt_pk_bf16_f32 v7, v20, v21
	global_store_dwordx2 v[4:5], v[6:7], off offset:64
	v_cvt_pk_bf16_f32 v0, v0, v1
	v_cvt_pk_bf16_f32 v1, v2, v3
	s_nop 4
	global_store_dwordx2 v[4:5], v[0:1], off offset:96
	s_waitcnt vmcnt(0)
	s_barrier
	v_mov_b32_e32 v24, v224
	v_mov_b32_e32 v25, v225
	v_mov_b32_e32 v26, v190
	v_mov_b32_e32 v27, v191
	v_mov_b32_e32 v28, v192
	v_mov_b32_e32 v29, v193

; __device__ __forceinline__ unsigned pk2(float lo, float hi) { return pg8::cvt_pk_bf16(lo, hi); }
; __device__ __forceinline__ f32x4 mma16(bf16x8 a, bf16x8 b, f32x4 c) { return __builtin_amdgcn_mfma_f32_16x16x32_bf16(a, b, c, 0, 0, 0); }
; #define BSYNC() do { asm volatile("s_waitcnt vmcnt(0) lgkmcnt(0)" ::: "memory"); __syncthreads(); } while (0)
; template <int TY> __device__ __forceinline__ void ma_even_item(const Params& p, ldsp lds, int item) {
;     ...
;     f32x4 acc[DK / 16];
; #pragma unroll
;     for (int i = 0; i < DK / 16; ++i) acc[i] = (f32x4){0.f, 0.f, 0.f, 0.f};
; #pragma unroll
;     for (int ks = 0; ks < 2; ++ks) { const bf16x8 bf = ldfrag(VT, (16 * wave + l15) * 72 + 32 * ks + 8 * q4);
; #pragma unroll
;         for (int i = 0; i < DK / 16; ++i) acc[i] = mma16(ldfrag(KHT, (16 * i + l15) * 72 + 32 * ks + 8 * q4), bf, acc[i]); }
;     bf16_t* HL = (bf16_t*)(p.ws + WS_HL + (TY ? HL_HGRN : 0)) + ((size_t)item * 128 + 16 * wave + l15) * DK;
; #pragma unroll
;     for (int i = 0; i < DK / 16; ++i) { u32x2 w; w.x = pk2(acc[i][0], acc[i][1]); w.y = pk2(acc[i][2], acc[i][3]); *(u32x2*)(HL + 16 * i + 4 * q4) = w; }
;     BSYNC();
.LBB0_1056:
	s_or_b64 exec, exec, s[0:1]
	v_and_b32_e32 v0, 63, v74
	v_lshrrev_b32_e32 v0, 1, v0
	v_and_b32_e32 v44, 15, v74
	v_and_b32_e32 v16, 24, v0
	v_mad_u32_u24 v4, v44, s53, v16
	v_lshl_add_u32 v4, v4, 1, 0
	s_waitcnt vmcnt(0) lgkmcnt(0)
	s_nop 0
	s_barrier
	ds_read_b128 v[186:189], v4 offset:40960
	s_lshl_b32 s0, s8, 4
	s_nop 0
	v_or_b32_e32 v1, s0, v44
	v_mad_u64_u32 v[0:1], s[8:9], v1, s53, v[16:17]
	v_lshl_add_u32 v40, v0, 1, 0
	ds_read_b128 v[190:193], v40 offset:59392
	s_nop 0
	v_mov_b32_e32 v36, 0x1f80
	v_mad_u32_u24 v51, v44, s53, v36
	v_add_u32_e32 v36, v16, v51
	v_lshl_add_u32 v36, v36, 1, 0
	ds_read_b128 v[194:197], v36 offset:40960
	s_nop 1
	s_waitcnt lgkmcnt(1)
	v_mfma_f32_16x16x32_bf16 v[30:33], v[186:189], v[190:193], 0
	v_mov_b32_e32 v4, 0x480
	v_mad_u32_u24 v45, v44, s53, v4
	v_add_u32_e32 v4, v16, v45
	v_lshl_add_u32 v4, v4, 1, 0
	ds_read_b128 v[186:189], v4 offset:40960
	s_nop 0
	v_or_b32_e32 v52, 32, v16
	s_nop 0
	s_waitcnt lgkmcnt(0)
	v_mfma_f32_16x16x32_bf16 v[26:29], v[186:189], v[190:193], 0
	v_mov_b32_e32 v4, 0x900
	v_mad_u32_u24 v46, v44, s53, v4
	v_add_u32_e32 v4, v16, v46
	v_lshl_add_u32 v4, v4, 1, 0
	ds_read_b128 v[186:189], v4 offset:40960
	s_nop 0
	v_lshlrev_b64 v[34:35], 7, v[34:35]
	s_nop 0
	s_waitcnt lgkmcnt(0)
	v_mfma_f32_16x16x32_bf16 v[22:25], v[186:189], v[190:193], 0
	v_mov_b32_e32 v4, 0xd80
	v_mad_u32_u24 v47, v44, s53, v4
	v_add_u32_e32 v4, v16, v47
	v_lshl_add_u32 v4, v4, 1, 0
	ds_read_b128 v[186:189], v4 offset:40960
	s_nop 0
	s_ashr_i32 s1, s0, 31
	s_nop 0
	s_waitcnt lgkmcnt(0)
	v_mfma_f32_16x16x32_bf16 v[18:21], v[186:189], v[190:193], 0
	v_mov_b32_e32 v4, 0x1200
	v_mad_u32_u24 v48, v44, s53, v4
	v_add_u32_e32 v4, v16, v48
	v_lshl_add_u32 v4, v4, 1, 0
	ds_read_b128 v[186:189], v4 offset:40960
	s_nop 0
	v_lshl_add_u64 v[34:35], v[34:35], 0, s[0:1]
	s_nop 0
	s_waitcnt lgkmcnt(0)
	v_mfma_f32_16x16x32_bf16 v[12:15], v[186:189], v[190:193], 0
	v_mov_b32_e32 v4, 0x1680
	v_mad_u32_u24 v49, v44, s53, v4
	v_add_u32_e32 v4, v16, v49
	v_lshl_add_u32 v4, v4, 1, 0
	ds_read_b128 v[186:189], v4 offset:40960
	s_nop 0
	v_or_b32_e32 v34, v34, v44
	s_nop 0
	s_waitcnt lgkmcnt(0)
	v_mfma_f32_16x16x32_bf16 v[8:11], v[186:189], v[190:193], 0
	v_mov_b32_e32 v4, 0x1b00
	v_mad_u32_u24 v50, v44, s53, v4
	v_add_u32_e32 v4, v16, v50
	v_lshl_add_u32 v4, v4, 1, 0
	ds_read_b128 v[186:189], v4 offset:40960
	ds_read_b128 v[206:209], v40 offset:59456
	s_nop 0
	v_readlane_b32 s0, v253, 55
	s_nop 0
	s_waitcnt lgkmcnt(1)
	v_mfma_f32_16x16x32_bf16 v[4:7], v[186:189], v[190:193], 0
	v_lshlrev_b64 v[34:35], 8, v[34:35]
	v_readlane_b32 s1, v253, 56
	v_mfma_f32_16x16x32_bf16 v[0:3], v[194:197], v[190:193], 0
	s_nop 0
	v_mad_u32_u24 v40, v44, s53, v52
	v_lshl_add_u32 v40, v40, 1, 0
	ds_read_b128 v[186:189], v40 offset:40960
	s_nop 0
	v_lshl_add_u64 v[34:35], s[0:1], 0, v[34:35]
	s_nop 0
	s_waitcnt lgkmcnt(0)
	v_mfma_f32_16x16x32_bf16 v[30:33], v[186:189], v[206:209], v[30:33]
	v_add_u32_e32 v40, v52, v45
	v_lshl_add_u32 v40, v40, 1, 0
	ds_read_b128 v[186:189], v40 offset:40960
	s_nop 0
	v_lshl_add_u64 v[34:35], v[34:35], 0, v[16:17]
	s_nop 0
	s_waitcnt lgkmcnt(0)
	v_mfma_f32_16x16x32_bf16 v[26:29], v[186:189], v[206:209], v[26:29]
	v_add_u32_e32 v40, v52, v46
	v_lshl_add_u32 v40, v40, 1, 0
	ds_read_b128 v[186:189], v40 offset:40960
	s_nop 1
	s_waitcnt lgkmcnt(0)
	v_mfma_f32_16x16x32_bf16 v[22:25], v[186:189], v[206:209], v[22:25]
	v_add_u32_e32 v40, v52, v47
	v_lshl_add_u32 v40, v40, 1, 0
	ds_read_b128 v[186:189], v40 offset:40960
	s_nop 1
	s_waitcnt lgkmcnt(0)
	v_mfma_f32_16x16x32_bf16 v[18:21], v[186:189], v[206:209], v[18:21]
	v_add_u32_e32 v40, v52, v48
	v_lshl_add_u32 v40, v40, 1, 0
	ds_read_b128 v[186:189], v40 offset:40960
	s_nop 1
	s_waitcnt lgkmcnt(0)
	v_mfma_f32_16x16x32_bf16 v[12:15], v[186:189], v[206:209], v[12:15]
	v_add_u32_e32 v40, v52, v49
	v_lshl_add_u32 v40, v40, 1, 0
	ds_read_b128 v[186:189], v40 offset:40960
	s_nop 1
	s_waitcnt lgkmcnt(0)
	v_mfma_f32_16x16x32_bf16 v[8:11], v[186:189], v[206:209], v[8:11]
	v_add_u32_e32 v40, v52, v50
	v_lshl_add_u32 v40, v40, 1, 0
	ds_read_b128 v[186:189], v40 offset:40960
	s_nop 1
	s_waitcnt lgkmcnt(0)
	v_mfma_f32_16x16x32_bf16 v[4:7], v[186:189], v[206:209], v[4:7]
	v_add_u32_e32 v40, v52, v51
	v_lshl_add_u32 v40, v40, 1, 0
	ds_read_b128 v[186:189], v40 offset:40960
	s_nop 0
	v_cvt_pk_bf16_f32 v30, v30, v31
	v_cvt_pk_bf16_f32 v31, v32, v33
	global_store_dwordx2 v[34:35], v[30:31], off
	s_nop 0
	s_waitcnt lgkmcnt(0)
	v_mfma_f32_16x16x32_bf16 v[0:3], v[186:189], v[206:209], v[0:3]
	v_cvt_pk_bf16_f32 v26, v26, v27
	v_cvt_pk_bf16_f32 v27, v28, v29
	global_store_dwordx2 v[34:35], v[26:27], off offset:32
	v_cvt_pk_bf16_f32 v22, v22, v23
	v_cvt_pk_bf16_f32 v23, v24, v25
	global_store_dwordx2 v[34:35], v[22:23], off offset:64
	v_cvt_pk_bf16_f32 v18, v18, v19
	v_cvt_pk_bf16_f32 v19, v20, v21
	global_store_dwordx2 v[34:35], v[18:19], off offset:96
	v_cvt_pk_bf16_f32 v12, v12, v13
	v_cvt_pk_bf16_f32 v13, v14, v15
	global_store_dwordx2 v[34:35], v[12:13], off offset:128
	v_cvt_pk_bf16_f32 v8, v8, v9
	v_cvt_pk_bf16_f32 v9, v10, v11
	global_store_dwordx2 v[34:35], v[8:9], off offset:160
	v_cvt_pk_bf16_f32 v4, v4, v5
	v_cvt_pk_bf16_f32 v5, v6, v7
	global_store_dwordx2 v[34:35], v[4:5], off offset:192
	v_cvt_pk_bf16_f32 v0, v0, v1
	v_cvt_pk_bf16_f32 v1, v2, v3
	s_nop 1
	global_store_dwordx2 v[34:35], v[0:1], off offset:224
	s_waitcnt vmcnt(0)
	s_barrier
	v_mov_b32_e32 v36, v206
	v_mov_b32_e32 v37, v207
	v_mov_b32_e32 v38, v208
	v_mov_b32_e32 v39, v209
	v_mov_b32_e32 v40, v186
	v_mov_b32_e32 v41, v187
	s_branch .LBB0_1049

; template <int F> __device__ __forceinline__ void stage_rows(ldsp dst, int dp, const bf16_t* src, size_t sp, int tid) {
;     constexpr int G8 = F / 8;
; #pragma unroll
; template <int TY> __device__ __forceinline__ void mc_item(const Params& p, ldsp lds, int item) {
;     ...
;     const int tid = otid(), lane = tid & 63, wave = __builtin_amdgcn_readfirstlane(tid >> 6), l15 = lane & 15, q4 = lane >> 4;
;     const int bh = item >> 5, c = item & 31, b = bh >> 2, h = bh & 3, sc = c / NB, jc = c % NB, row0 = b * 2048 + c * 64;
;     ...
;     if (TY != 2) lds += LDSSHIFT;
;     ...
;     ldsp QX = lds, QH2 = lds + o_qh, KTs = lds + o_kt, VTs = lds + o_vt, Pm = lds + o_pm; LAS float* RED = (LAS float*)(lds + o_red);
;     const bf16_t* Pb = (const bf16_t*)(p.ws + WS_P);
;     constexpr int PP = TY == 2 ? NO : NE;
;     const int ecol = TY ? 256 + h * 128 : h * 64;
;     if (TY == 2) stage_rows<DK>(QX, PQ, Pb + (size_t)row0 * NO + O_Q + h * 256, NO, tid);
;     else { stage_rows<DK>(QX, PQ, (const bf16_t*)(p.ws + WS_QT) + (size_t)row0 * 768 + ecol, 768, tid);
;            stage_rows<DK>(QH2, PQ, (const bf16_t*)(p.ws + WS_QH) + (size_t)row0 * 768 + ecol, 768, tid); }
;     f32x4 acc[ET][4];
; #pragma unroll
;     for (int ei = 0; ei < ET; ++ei)
; #pragma unroll
;         for (int tk = 0; tk < 4; ++tk) acc[ei][tk] = (f32x4){0.f, 0.f, 0.f, 0.f};
;     const int voff = TY == 0 ? E_VA + h * 128 : (TY == 1 ? E_IB + h * 128 : O_V + h * 512);
;     const int tt = wave & 3, sp = wave >> 2;
;     u32x4 kr[TY == 2 ? 4 : 1], vr[TY == 2 ? 8 : 1];
;     if constexpr (TY == 2) { const size_t rowq = (size_t)b * 2048 + (sc * NB) * 64;
;         ld_rows<256>(kr, Pb + rowq * NO + O_K + h * 256, NO, tid); ld_T<512>(vr, Pb + rowq * NO + voff, NO, wave, lane); }
;     for (int j = 0; j <= jc; ++j) { const size_t rowj = (size_t)b * 2048 + (sc * NB + j) * 64;
;         if constexpr (TY == 2) { st_rows<256>(KTs, PQ, kr, tid); st_T<512>(VTs, 72, vr, wave, lane); }
;         else { stage_rows<DK>(KTs, PQ, (const bf16_t*)(p.ws + WS_KT) + rowj * 768 + ecol, 768, tid);
;                stage_T<DV>(VTs, 72, Pb + rowj * PP + voff, PP, wave, lane); }
;         if constexpr (TY == 2) { __syncthreads(); if (j < jc) { const size_t rown = rowj + 64; ld_rows<256>(kr, Pb + rown * NO + O_K + h * 256, NO, tid); ld_T<512>(vr, Pb + rown * NO + voff, NO, wave, lane); } }
;         else BSYNC();
.LBB0_1243:
	s_lshl_b32 s1, s12, 11
	v_readlane_b32 s20, v254, 1
	s_or_b32 s17, s1, s20
	s_lshl_b32 s1, s8, 7
	v_mov_b32_e32 v22, v161
	s_and_b32 s1, s1, 0x180
	s_mul_i32 s13, s17, 0x600
	s_mul_hi_i32 s9, s17, 0x600
	s_add_u32 s18, s28, s13
	v_add_u32_e32 v6, 0x200, v22
	s_addc_u32 s19, s29, s9
	s_lshl_b32 s16, s1, 1
	v_ashrrev_i32_e32 v0, 31, v22
	v_ashrrev_i32_e32 v7, 31, v6
	s_add_u32 s18, s18, s16
	v_lshrrev_b32_e32 v0, 28, v0
	v_lshrrev_b32_e32 v7, 28, v7
	s_addc_u32 s19, s19, 0
	v_add_u32_e32 v0, v22, v0
	v_add_u32_e32 v7, v6, v7
	v_ashrrev_i32_e32 v23, 4, v0
	v_and_b32_e32 v0, 0x1ffffff0, v0
	v_mov_b64_e32 v[4:5], s[18:19]
	v_ashrrev_i32_e32 v42, 4, v7
	s_add_u32 s1, s22, s13
	v_sub_u32_e32 v2, v22, v0
	v_mad_i64_i32 v[0:1], s[18:19], v23, s60, v[4:5]
	v_mad_i64_i32 v[4:5], s[18:19], v42, s60, v[4:5]
	s_addc_u32 s9, s23, s9
	s_add_u32 s18, s1, s16
	s_addc_u32 s19, s9, 0
	v_mov_b64_e32 v[12:13], s[18:19]
	v_mad_i64_i32 v[8:9], s[18:19], v23, s60, v[12:13]
	v_mad_i64_i32 v[12:13], s[18:19], v42, s60, v[12:13]
	s_ashr_i32 s13, s12, 31
	s_lshl_b64 s[18:19], s[12:13], 11
	s_or_b32 s9, s18, s20
	s_mul_i32 s13, s19, 0x600
	s_mul_hi_u32 s18, s9, 0x600
	v_readfirstlane_b32 s0, v22
	s_add_i32 s20, s18, s13
	s_mul_i32 s13, s19, 0x1e00
	s_mul_hi_u32 s18, s9, 0x1e00
	s_ashr_i32 s1, s0, 6
	s_mul_i32 s21, s9, 0x600
	s_add_i32 s18, s18, s13
	s_mulk_i32 s9, 0x1e00
	v_and_b32_e32 v7, 0x1ffffff0, v7
	s_add_u32 s9, s26, s9
	v_sub_u32_e32 v6, v6, v7
	s_addc_u32 s13, s27, s18
	v_lshlrev_b32_e32 v40, 3, v6
	s_add_u32 s18, s9, s16
	v_ashrrev_i32_e32 v41, 31, v40
	s_addc_u32 s19, s13, 0
	s_lshl_b32 s9, s1, 5
	v_and_b32_e32 v16, 31, v22
	v_lshlrev_b64 v[24:25], 1, v[40:41]
	v_and_or_b32 v41, s9, 32, v16
	v_mul_u32_u24_e32 v16, 0xf00, v41
	v_lshlrev_b32_e32 v16, 1, v16
	v_lshl_add_u64 v[20:21], s[18:19], 0, v[16:17]
	v_bfe_u32 v16, v22, 5, 1
	v_lshlrev_b32_e32 v38, 3, v2
	v_and_or_b32 v16, s1, -2, v16
	s_lshl_b32 s13, s1, 4
	s_ashr_i32 s1, s0, 3
	v_ashrrev_i32_e32 v39, 31, v38
	s_andn2_b32 s1, s1, 31
	v_lshlrev_b64 v[18:19], 1, v[38:39]
	s_add_u32 s9, s72, s21
	v_lshl_add_u64 v[0:1], v[0:1], 0, v[18:19]
	s_addc_u32 s19, s73, s20
	global_load_dwordx4 v[0:3], v[0:1], off offset:512
	v_lshlrev_b32_e32 v26, 3, v16
	s_add_u32 s18, s9, s16
	v_lshl_add_u64 v[4:5], v[4:5], 0, v[24:25]
	v_ashrrev_i32_e32 v27, 31, v26
	s_addc_u32 s19, s19, 0
	global_load_dwordx4 v[4:7], v[4:5], off offset:512
	v_lshl_add_u64 v[8:9], v[8:9], 0, v[18:19]
	v_lshl_add_u64 v[34:35], v[26:27], 1, v[20:21]
	v_mov_b64_e32 v[26:27], s[18:19]
	global_load_dwordx4 v[8:11], v[8:9], off offset:512
	v_lshl_add_u64 v[12:13], v[12:13], 0, v[24:25]
	v_mad_i64_i32 v[20:21], s[18:19], v23, s60, v[26:27]
	v_mad_i64_i32 v[26:27], s[18:19], v42, s60, v[26:27]
	global_load_dwordx4 v[12:15], v[12:13], off offset:512
	v_lshl_add_u64 v[18:19], v[20:21], 0, v[18:19]
	v_lshl_add_u64 v[24:25], v[26:27], 0, v[24:25]
	global_load_dwordx4 v[18:21], v[18:19], off offset:512
	s_mov_b64 s[18:19], 0x1400
	global_load_dwordx4 v[26:29], v[24:25], off offset:512
	v_add_co_u32_e32 v24, vcc, s57, v34
	s_movk_i32 s20, 0x88
	s_nop 0
	v_addc_co_u32_e32 v25, vcc, 0, v35, vcc
	global_load_dwordx4 v[30:33], v[24:25], off offset:1024
	v_lshl_add_u64 v[24:25], v[34:35], 0, s[18:19]
	global_load_dwordx4 v[34:37], v[24:25], off offset:128
	v_mad_u64_u32 v[38:39], s[18:19], v23, s20, v[38:39]
	v_lshl_add_u32 v23, v38, 1, 0
	s_movk_i32 s9, 0x240
	v_and_b32_e32 v24, 15, v22
	v_and_b32_e32 v25, 48, v22
	s_waitcnt vmcnt(0)
	ds_write_b128 v23, v[0:3]
	v_mad_u64_u32 v[0:1], s[18:19], v42, s20, v[40:41]
	v_lshl_add_u32 v2, v0, 1, 0
	v_mul_lo_u32 v0, v16, s9
	ds_write_b128 v2, v[4:7]
	ds_write_b128 v23, v[8:11] offset:17408
	ds_write_b128 v2, v[12:15] offset:17408
	v_bfe_u32 v9, v22, 4, 2
	v_or_b32_e32 v0, v41, v0
	v_lshl_add_u32 v3, v0, 1, 0
	v_lshlrev_b32_e32 v8, 3, v9
	v_or_b32_e32 v0, s1, v24
	v_mad_u64_u32 v[0:1], s[18:19], v0, s20, v[8:9]
	ds_write_b128 v23, v[18:21] offset:34816
	ds_write_b128 v2, v[26:29] offset:34816
	ds_write_b16 v3, v30 offset:52224
	ds_write_b16_d16_hi v3, v30 offset:52368
	ds_write_b16 v3, v31 offset:52512
	ds_write_b16_d16_hi v3, v31 offset:52656
	ds_write_b16 v3, v32 offset:52800
	ds_write_b16_d16_hi v3, v32 offset:52944
	ds_write_b16 v3, v33 offset:53088
	ds_write_b16_d16_hi v3, v33 offset:53232
	ds_write_b16 v3, v34 offset:61440
	ds_write_b16_d16_hi v3, v34 offset:61584
	ds_write_b16 v3, v35 offset:61728
	ds_write_b16_d16_hi v3, v35 offset:61872
	ds_write_b16 v3, v36 offset:62016
	ds_write_b16_d16_hi v3, v36 offset:62160
	ds_write_b16 v3, v37 offset:62304
	ds_write_b16_d16_hi v3, v37 offset:62448
	v_lshl_add_u32 v14, v0, 1, 0
	s_waitcnt vmcnt(0) lgkmcnt(0)
	s_nop 0
	s_barrier
; #define LAS __attribute__((address_space(3)))
; __device__ __forceinline__ unsigned pk2(float lo, float hi) { return pg8::cvt_pk_bf16(lo, hi); }
; __device__ __forceinline__ f32x4 mma16(bf16x8 a, bf16x8 b, f32x4 c) { return __builtin_amdgcn_mfma_f32_16x16x32_bf16(a, b, c, 0, 0, 0); }
; template <int TY> __device__ __forceinline__ void mc_item(const Params& p, ldsp lds, int item) {
;     ...
;         { f32x4 c0 = (f32x4){0.f, 0.f, 0.f, 0.f}, c1 = c0;
; #pragma unroll
;           for (int ks = 0; ks < DK / 32; ++ks) { const bf16x8 bq = ldfrag(QX, (16 * tt + l15) * PQ + 32 * ks + 8 * q4);
;               c0 = mma16(ldfrag(KTs, (16 * (2 * sp) + l15) * PQ + 32 * ks + 8 * q4), bq, c0);
;               c1 = mma16(ldfrag(KTs, (16 * (2 * sp + 1) + l15) * PQ + 32 * ks + 8 * q4), bq, c1); }
;           const int t = 16 * tt + l15;
;           const int tl = (j == jc) ? t : 4096;
; #pragma unroll
;           for (int jj = 0; jj < 4; ++jj) { if (32 * sp + 4 * q4 + jj > tl) c0[jj] = 0.f; if (32 * sp + 16 + 4 * q4 + jj > tl) c1[jj] = 0.f; }
;           u32x2 w; w.x = pk2(c0[0], c0[1]); w.y = pk2(c0[2], c0[3]); *(LAS u32x2*)(Pm + (size_t)(t * 72 + 32 * sp + 4 * q4) * 2) = w;
;           w.x = pk2(c1[0], c1[1]); w.y = pk2(c1[2], c1[3]); *(LAS u32x2*)(Pm + (size_t)(t * 72 + 32 * sp + 16 + 4 * q4) * 2) = w; }
;         if constexpr (TY == 2) __syncthreads(); else BSYNC();
; #pragma unroll
;         for (int ks = 0; ks < 2; ++ks) { bf16x8 pb[4];
; #pragma unroll
;             for (int tk = 0; tk < 4; ++tk) pb[tk] = ldfrag(Pm, (16 * tk + l15) * 72 + 32 * ks + 8 * q4);
; #pragma unroll
;             for (int ei = 0; ei < ET; ++ei) { const bf16x8 va = ldfrag(VTs, (16 * (wave * ET + ei) + l15) * 72 + 32 * ks + 8 * q4);
; #pragma unroll
;                 for (int tk = 0; tk < 4; ++tk) acc[ei][tk] = mma16(va, pb[tk], acc[ei][tk]); } }
;         if constexpr (TY == 2) __syncthreads(); else BSYNC(); }
;     if ((TY == 2 ? sc : c) != 0) { const bf16_t* STp = (TY == 2) ? (const bf16_t*)(p.ws + WS_ST) + ((size_t)bh * 8 + sc) * 512 * 256
;                                     : (const bf16_t*)(p.ws + WS_ST + (TY ? ST_HGRN : 0)) + ((size_t)bh * 32 + c) * 128 * DK;
;       ldsp QS = (TY == 2) ? QX : QH2;
;       bf16x8 sa[ET], sn[ET];
; #pragma unroll
;       for (int ei = 0; ei < ET; ++ei) sa[ei] = *(const bf16x8*)(STp + (size_t)(16 * (wave * ET + ei) + l15) * DK + 8 * q4);
	ds_read_b128 v[26:29], v14 offset:34816
	s_nop 0
	v_and_or_b32 v15, s13, 48, v24
	v_mad_u32_u24 v4, v15, s20, v8
	v_lshl_add_u32 v16, v4, 1, 0
	ds_read_b128 v[34:37], v16
	ds_read_b128 v[186:189], v14 offset:39168
	ds_read_b128 v[190:193], v14 offset:34880
	ds_read_b128 v[194:197], v16 offset:64
	ds_read_b128 v[206:209], v14 offset:39232
	ds_read_b128 v[218:221], v14 offset:34944
	ds_read_b128 v[222:225], v16 offset:128
	ds_read_b128 v[226:229], v14 offset:39296
	ds_read_b128 v[230:233], v14 offset:35008
	ds_read_b128 v[234:237], v16 offset:192
	ds_read_b128 v[238:241], v14 offset:39360
	s_nop 3
	s_waitcnt lgkmcnt(10)
	v_mfma_f32_16x16x32_bf16 v[0:3], v[26:29], v[34:37], 0
	v_lshlrev_b32_e32 v23, 2, v9
	v_or_b32_e32 v9, s1, v23
	v_cmp_gt_i32_e32 vcc, v9, v15
	s_nop 0
	s_waitcnt lgkmcnt(9)
	v_mfma_f32_16x16x32_bf16 v[4:7], v[186:189], v[34:37], 0
	s_nop 1
	v_readlane_b32 s9, v255, 24
	s_movk_i32 s1, 0x90
	s_nop 0
	s_waitcnt lgkmcnt(7)
	v_mfma_f32_16x16x32_bf16 v[0:3], v[190:193], v[194:197], v[0:3]
	s_nop 1
	s_waitcnt lgkmcnt(6)
	v_mfma_f32_16x16x32_bf16 v[4:7], v[206:209], v[194:197], v[4:7]
	s_nop 1
	s_waitcnt lgkmcnt(4)
	v_mfma_f32_16x16x32_bf16 v[0:3], v[218:221], v[222:225], v[0:3]
	s_nop 2
	s_waitcnt lgkmcnt(3)
	v_mfma_f32_16x16x32_bf16 v[4:7], v[226:229], v[222:225], v[4:7]
	s_nop 1
	v_mad_u32_u24 v14, v15, s53, v9
	v_lshl_add_u32 v14, v14, 1, s9
	s_nop 0
	s_waitcnt lgkmcnt(1)
	v_mfma_f32_16x16x32_bf16 v[0:3], v[230:233], v[234:237], v[0:3]
	s_nop 0
	s_waitcnt lgkmcnt(0)
	v_mfma_f32_16x16x32_bf16 v[4:7], v[238:241], v[234:237], v[4:7]
	v_mov_b32_e32 v12, s41
	s_nop 4
	v_cndmask_b32_e32 v13, v0, v12, vcc
	v_or_b32_e32 v12, 16, v9
	v_cmp_gt_i32_e32 vcc, v12, v15
	v_mov_b32_e32 v12, s41
	v_or_b32_e32 v10, s13, v24
	v_cndmask_b32_e32 v4, v4, v12, vcc
	v_cmp_lt_i32_e32 vcc, v9, v15
	v_or_b32_e32 v12, 17, v9
	v_mul_lo_u32 v11, v10, s1
	v_cndmask_b32_e32 v0, v13, v0, vcc
	v_cndmask_b32_e32 v1, 0, v1, vcc
	v_cmp_le_i32_e32 vcc, v12, v15
	v_or_b32_e32 v12, 2, v9
	v_cvt_pk_bf16_f32 v0, v0, v1
	s_nop 0
	v_cndmask_b32_e32 v5, 0, v5, vcc
	v_cmp_le_i32_e32 vcc, v12, v15
	v_or_b32_e32 v12, 18, v9
	s_nop 0
	v_cndmask_b32_e32 v2, 0, v2, vcc
	v_cmp_le_i32_e32 vcc, v12, v15
	v_or_b32_e32 v12, 3, v9
	v_or_b32_e32 v9, 19, v9
	v_cndmask_b32_e32 v6, 0, v6, vcc
	v_cmp_le_i32_e32 vcc, v12, v15
	s_nop 1
	v_cndmask_b32_e32 v3, 0, v3, vcc
	v_cmp_le_i32_e32 vcc, v9, v15
	v_cvt_pk_bf16_f32 v1, v2, v3
	v_add3_u32 v9, 0, v25, v11
	ds_write_b64 v14, v[0:1]
	v_cndmask_b32_e32 v7, 0, v7, vcc
	v_cvt_pk_bf16_f32 v0, v4, v5
	v_cvt_pk_bf16_f32 v1, v6, v7
	ds_write_b64 v14, v[0:1] offset:32
	s_waitcnt vmcnt(0)
	s_nop 0
	s_waitcnt lgkmcnt(0)
	s_barrier
	ds_read_b128 v[26:29], v9 offset:52224
	s_nop 0
	v_mul_u32_u24_e32 v4, 0x90, v24
	v_add3_u32 v11, s9, v25, v4
	ds_read_b128 v[34:37], v11
	ds_read_b128 v[186:189], v11 offset:2304
	ds_read_b128 v[190:193], v11 offset:4608
	ds_read_b128 v[194:197], v11 offset:6912
	ds_read_b128 v[206:209], v9 offset:52288
	ds_read_b128 v[218:221], v11 offset:64
	ds_read_b128 v[222:225], v11 offset:2368
	ds_read_b128 v[226:229], v11 offset:6976
	ds_read_b128 v[230:233], v11 offset:4672
	s_nop 5
	s_waitcnt lgkmcnt(6)
	v_mfma_f32_16x16x32_bf16 v[30:33], v[26:29], v[190:193], 0
	s_nop 0
	s_and_b64 vcc, exec, s[10:11]
	v_mfma_f32_16x16x32_bf16 v[4:7], v[26:29], v[34:37], 0
	s_nop 0
	s_waitcnt lgkmcnt(3)
	v_mfma_f32_16x16x32_bf16 v[18:21], v[206:209], v[218:221], v[4:7]
	v_mfma_f32_16x16x32_bf16 v[12:15], v[26:29], v[186:189], 0
	s_nop 5
	v_mfma_f32_16x16x32_bf16 v[0:3], v[26:29], v[194:197], 0
	s_nop 1
	s_waitcnt lgkmcnt(2)
	v_mfma_f32_16x16x32_bf16 v[12:15], v[206:209], v[222:225], v[12:15]
	s_nop 0
	s_waitcnt vmcnt(0)
	s_nop 0
	s_waitcnt lgkmcnt(0)
	v_mfma_f32_16x16x32_bf16 v[4:7], v[206:209], v[230:233], v[30:33]
	s_barrier
	v_mfma_f32_16x16x32_bf16 v[0:3], v[206:209], v[226:229], v[0:3]
	s_cbranch_vccnz .LBB0_1246
	s_ashr_i32 s9, s8, 31
	s_lshl_b64 s[18:19], s[8:9], 20
	v_readlane_b32 s1, v254, 5
	s_add_u32 s18, s1, s18
	v_readlane_b32 s1, v254, 7
	v_ashrrev_i32_e32 v11, 31, v10
	s_addc_u32 s19, s1, s19
	v_lshlrev_b64 v[10:11], 8, v[10:11]
	v_lshl_add_u64 v[10:11], s[18:19], 0, v[10:11]
	v_lshlrev_b32_e32 v16, 1, v8
	v_lshl_add_u64 v[8:9], v[10:11], 0, v[16:17]
	v_mul_u32_u24_e32 v10, 0x110, v24
	s_add_i32 s1, 0, 0x4400
	v_add3_u32 v16, v10, v25, s1
	s_mov_b32 s1, 32
	v_mov_b64_e32 v[10:11], v[8:9]

; template <int F> __device__ __forceinline__ void stage_rows(ldsp dst, int dp, const bf16_t* src, size_t sp, int tid) {
;     constexpr int G8 = F / 8;
; #pragma unroll
; template <int TY> __device__ __forceinline__ void mc_item(const Params& p, ldsp lds, int item) {
;     ...
;     const int tid = otid(), lane = tid & 63, wave = __builtin_amdgcn_readfirstlane(tid >> 6), l15 = lane & 15, q4 = lane >> 4;
;     const int bh = item >> 5, c = item & 31, b = bh >> 2, h = bh & 3, sc = c / NB, jc = c % NB, row0 = b * 2048 + c * 64;
;     ...
;     if (TY != 2) lds += LDSSHIFT;
;     ...
;     ldsp QX = lds, QH2 = lds + o_qh, KTs = lds + o_kt, VTs = lds + o_vt, Pm = lds + o_pm; LAS float* RED = (LAS float*)(lds + o_red);
;     const bf16_t* Pb = (const bf16_t*)(p.ws + WS_P);
;     constexpr int PP = TY == 2 ? NO : NE;
;     const int ecol = TY ? 256 + h * 128 : h * 64;
;     if (TY == 2) stage_rows<DK>(QX, PQ, Pb + (size_t)row0 * NO + O_Q + h * 256, NO, tid);
;     else { stage_rows<DK>(QX, PQ, (const bf16_t*)(p.ws + WS_QT) + (size_t)row0 * 768 + ecol, 768, tid);
;            stage_rows<DK>(QH2, PQ, (const bf16_t*)(p.ws + WS_QH) + (size_t)row0 * 768 + ecol, 768, tid); }
;     f32x4 acc[ET][4];
; #pragma unroll
;     for (int ei = 0; ei < ET; ++ei)
; #pragma unroll
;         for (int tk = 0; tk < 4; ++tk) acc[ei][tk] = (f32x4){0.f, 0.f, 0.f, 0.f};
;     const int voff = TY == 0 ? E_VA + h * 128 : (TY == 1 ? E_IB + h * 128 : O_V + h * 512);
;     const int tt = wave & 3, sp = wave >> 2;
;     u32x4 kr[TY == 2 ? 4 : 1], vr[TY == 2 ? 8 : 1];
;     if constexpr (TY == 2) { const size_t rowq = (size_t)b * 2048 + (sc * NB) * 64;
;         ld_rows<256>(kr, Pb + rowq * NO + O_K + h * 256, NO, tid); ld_T<512>(vr, Pb + rowq * NO + voff, NO, wave, lane); }
;     for (int j = 0; j <= jc; ++j) { const size_t rowj = (size_t)b * 2048 + (sc * NB + j) * 64;
;         if constexpr (TY == 2) { st_rows<256>(KTs, PQ, kr, tid); st_T<512>(VTs, 72, vr, wave, lane); }
;         else { stage_rows<DK>(KTs, PQ, (const bf16_t*)(p.ws + WS_KT) + rowj * 768 + ecol, 768, tid);
;                stage_T<DV>(VTs, 72, Pb + rowj * PP + voff, PP, wave, lane); }
;         if constexpr (TY == 2) { __syncthreads(); if (j < jc) { const size_t rown = rowj + 64; ld_rows<256>(kr, Pb + rown * NO + O_K + h * 256, NO, tid); ld_T<512>(vr, Pb + rown * NO + voff, NO, wave, lane); } }
;         else BSYNC();
.LBB0_1255:
	s_lshl_b32 s0, s12, 11
	v_readlane_b32 s19, v254, 1
	s_or_b32 s16, s0, s19
	v_mov_b32_e32 v27, v161
	s_bfe_u32 s9, s15, 0x20005
	s_mul_i32 s18, s16, 0x600
	s_mul_hi_i32 s13, s16, 0x600
	s_add_u32 s0, s28, s18
	v_ashrrev_i32_e32 v0, 31, v27
	s_addc_u32 s1, s29, s13
	s_lshl_b32 s15, s9, 7
	v_lshrrev_b32_e32 v0, 29, v0
	s_add_u32 s0, s0, s15
	v_add_u32_e32 v0, v27, v0
	s_addc_u32 s1, s1, 0
	v_ashrrev_i32_e32 v24, 3, v0
	v_and_b32_e32 v0, 0x1ffffff8, v0
	v_sub_u32_e32 v2, v27, v0
	v_mov_b64_e32 v[0:1], s[0:1]
	v_mad_i64_i32 v[0:1], s[0:1], v24, s60, v[0:1]
	s_add_u32 s0, s22, s18
	s_addc_u32 s1, s23, s13
	s_add_u32 s0, s0, s15
	s_addc_u32 s1, s1, 0
	v_mov_b64_e32 v[4:5], s[0:1]
	v_mad_i64_i32 v[4:5], s[0:1], v24, s60, v[4:5]
	s_ashr_i32 s13, s12, 31
	s_lshl_b64 s[0:1], s[12:13], 11
	s_or_b32 s0, s0, s19
	s_mul_i32 s12, s1, 0x600
	s_mul_hi_u32 s13, s0, 0x600
	v_readfirstlane_b32 s17, v27
	s_add_i32 s13, s13, s12
	s_mulk_i32 s1, 0x1e00
	s_mul_hi_u32 s12, s0, 0x1e00
	s_ashr_i32 s18, s17, 6
	s_mul_i32 s19, s0, 0x600
	s_add_i32 s12, s12, s1
	s_mulk_i32 s0, 0x1e00
	s_add_u32 s0, s26, s0
	s_addc_u32 s1, s27, s12
	s_lshl_b32 s9, s9, 8
	s_add_u32 s0, s0, s9
	s_addc_u32 s1, s1, 0
	s_lshl_b32 s9, s18, 5
	v_and_b32_e32 v10, 31, v27
	v_and_or_b32 v25, s9, 32, v10
	v_mul_u32_u24_e32 v10, 0xf00, v25
	v_lshlrev_b32_e32 v16, 1, v10
	v_lshl_add_u64 v[10:11], s[0:1], 0, v[16:17]
	s_ashr_i32 s0, s17, 3
	s_lshl_b32 s12, s18, 4
	s_and_b32 s9, s0, 0xffffffe0
	v_bfe_u32 v12, v27, 5, 1
	s_add_u32 s0, s72, s19
	v_and_or_b32 v26, s18, -2, v12
	s_addc_u32 s1, s73, s13
	v_lshlrev_b32_e32 v12, 3, v26
	s_add_u32 s0, s0, s15
	v_lshlrev_b32_e32 v22, 3, v2
	v_ashrrev_i32_e32 v13, 31, v12
	s_addc_u32 s1, s1, 0
	v_ashrrev_i32_e32 v23, 31, v22
	v_lshl_add_u64 v[18:19], v[12:13], 1, v[10:11]
	v_mov_b64_e32 v[10:11], s[0:1]
	v_lshlrev_b64 v[8:9], 1, v[22:23]
	v_mad_i64_i32 v[10:11], s[0:1], v24, s60, v[10:11]
	v_lshl_add_u64 v[0:1], v[0:1], 0, v[8:9]
	v_lshl_add_u64 v[4:5], v[4:5], 0, v[8:9]
	v_lshl_add_u64 v[8:9], v[10:11], 0, v[8:9]
	global_load_dwordx4 v[0:3], v[0:1], off
	v_mad_u64_u32 v[22:23], s[0:1], v24, s53, v[22:23]
	global_load_dwordx4 v[4:7], v[4:5], off
	s_nop 0
	global_load_dwordx4 v[8:11], v[8:9], off
	s_nop 0
	global_load_dwordx4 v[12:15], v[18:19], off offset:1024
	s_nop 0
	global_load_dwordx4 v[18:21], v[18:19], off offset:1152
	s_movk_i32 s0, 0x240
	v_and_b32_e32 v30, 15, v27
	v_bfe_u32 v28, v27, 4, 2
	v_lshl_add_u32 v24, v22, 1, 0
	v_mul_lo_u32 v22, v26, s0
	v_lshlrev_b32_e32 v16, 3, v28
	v_or_b32_e32 v22, v25, v22
	v_or_b32_e32 v23, s9, v30
	v_lshl_add_u32 v25, v22, 1, 0
	v_mad_u64_u32 v[22:23], s[0:1], v23, s53, v[16:17]
	v_lshl_add_u32 v22, v22, 1, 0
	v_and_or_b32 v29, s12, 48, v30
	v_lshlrev_b32_e32 v28, 2, v28
	s_waitcnt vmcnt(0)
	ds_write_b128 v24, v[0:3]
	ds_write_b128 v24, v[4:7] offset:9216
	ds_write_b128 v24, v[8:11] offset:18432
	ds_write_b16 v25, v12 offset:27648
	ds_write_b16_d16_hi v25, v12 offset:27792
	ds_write_b16 v25, v13 offset:27936
	ds_write_b16_d16_hi v25, v13 offset:28080
	ds_write_b16 v25, v14 offset:28224
	ds_write_b16_d16_hi v25, v14 offset:28368
	ds_write_b16 v25, v15 offset:28512
	ds_write_b16_d16_hi v25, v15 offset:28656
	ds_write_b16 v25, v18 offset:36864
	ds_write_b16_d16_hi v25, v18 offset:37008
	ds_write_b16 v25, v19 offset:37152
	ds_write_b16_d16_hi v25, v19 offset:37296
	ds_write_b16 v25, v20 offset:37440
	ds_write_b16_d16_hi v25, v20 offset:37584
	ds_write_b16 v25, v21 offset:37728
	ds_write_b16_d16_hi v25, v21 offset:37872
	s_waitcnt vmcnt(0) lgkmcnt(0)
	s_nop 0
	s_barrier
; template <int TY> __device__ __forceinline__ void mc_item(const Params& p, ldsp lds, int item) {
;     ...
;         { f32x4 c0 = (f32x4){0.f, 0.f, 0.f, 0.f}, c1 = c0;
; #pragma unroll
;           for (int ks = 0; ks < DK / 32; ++ks) { const bf16x8 bq = ldfrag(QX, (16 * tt + l15) * PQ + 32 * ks + 8 * q4);
;               c0 = mma16(ldfrag(KTs, (16 * (2 * sp) + l15) * PQ + 32 * ks + 8 * q4), bq, c0);
;               c1 = mma16(ldfrag(KTs, (16 * (2 * sp + 1) + l15) * PQ + 32 * ks + 8 * q4), bq, c1); }
;           const int t = 16 * tt + l15;
;           const int tl = (j == jc) ? t : 4096;
; #pragma unroll
;           for (int jj = 0; jj < 4; ++jj) { if (32 * sp + 4 * q4 + jj > tl) c0[jj] = 0.f; if (32 * sp + 16 + 4 * q4 + jj > tl) c1[jj] = 0.f; }
;           u32x2 w; w.x = pk2(c0[0], c0[1]); w.y = pk2(c0[2], c0[3]); *(LAS u32x2*)(Pm + (size_t)(t * 72 + 32 * sp + 4 * q4) * 2) = w;
;           w.x = pk2(c1[0], c1[1]); w.y = pk2(c1[2], c1[3]); *(LAS u32x2*)(Pm + (size_t)(t * 72 + 32 * sp + 16 + 4 * q4) * 2) = w; }
;         if constexpr (TY == 2) __syncthreads(); else BSYNC();
; #pragma unroll
;         for (int ks = 0; ks < 2; ++ks) { bf16x8 pb[4];
; #pragma unroll
;             for (int tk = 0; tk < 4; ++tk) pb[tk] = ldfrag(Pm, (16 * tk + l15) * 72 + 32 * ks + 8 * q4);
; #pragma unroll
;             for (int ei = 0; ei < ET; ++ei) { const bf16x8 va = ldfrag(VTs, (16 * (wave * ET + ei) + l15) * 72 + 32 * ks + 8 * q4);
; #pragma unroll
;                 for (int tk = 0; tk < 4; ++tk) acc[ei][tk] = mma16(va, pb[tk], acc[ei][tk]); } }
;         if constexpr (TY == 2) __syncthreads(); else BSYNC(); }
;     if ((TY == 2 ? sc : c) != 0) { const bf16_t* STp = (TY == 2) ? (const bf16_t*)(p.ws + WS_ST) + ((size_t)bh * 8 + sc) * 512 * 256
;                                     : (const bf16_t*)(p.ws + WS_ST + (TY ? ST_HGRN : 0)) + ((size_t)bh * 32 + c) * 128 * DK;
;       ldsp QS = (TY == 2) ? QX : QH2;
;       bf16x8 sa[ET], sn[ET];
; #pragma unroll
;       for (int ei = 0; ei < ET; ++ei) sa[ei] = *(const bf16x8*)(STp + (size_t)(16 * (wave * ET + ei) + l15) * DK + 8 * q4);
; #pragma unroll 1
;       for (int ks = 0; ks < DK / 32; ++ks) { bf16x8 qb[4];
;           const int kn = (ks + 1 < DK / 32) ? ks + 1 : ks;
; #pragma unroll
;           for (int ei = 0; ei < ET; ++ei) sn[ei] = *(const bf16x8*)(STp + (size_t)(16 * (wave * ET + ei) + l15) * DK + 32 * kn + 8 * q4);
	ds_read_b128 v[36:39], v22 offset:18432
	s_nop 0
	v_mad_u32_u24 v4, v29, s53, v16
	v_lshl_add_u32 v18, v4, 1, 0
	ds_read_b128 v[186:189], v18
	ds_read_b128 v[190:193], v22 offset:20736
	ds_read_b128 v[194:197], v22 offset:18496
	ds_read_b128 v[206:209], v18 offset:64
	ds_read_b128 v[218:221], v22 offset:20800
	s_nop 2
	s_waitcnt lgkmcnt(4)
	v_mfma_f32_16x16x32_bf16 v[0:3], v[36:39], v[186:189], 0
	s_nop 3
	s_waitcnt lgkmcnt(3)
	v_mfma_f32_16x16x32_bf16 v[4:7], v[190:193], v[186:189], 0
	v_or_b32_e32 v9, s9, v28
	v_mad_u32_u24 v8, v29, s53, v9
	v_lshl_add_u32 v10, v8, 1, 0
	s_nop 0
	s_waitcnt lgkmcnt(1)
	v_mfma_f32_16x16x32_bf16 v[0:3], v[194:197], v[206:209], v[0:3]
	v_and_b32_e32 v8, 48, v27
	v_add_u32_e32 v26, 0, v8
	v_cmp_gt_i32_e32 vcc, v9, v29
	s_nop 0
	s_waitcnt lgkmcnt(0)
	v_mfma_f32_16x16x32_bf16 v[4:7], v[218:221], v[206:209], v[4:7]
	v_mov_b32_e32 v8, s41
	s_nop 1
	v_cndmask_b32_e32 v11, v0, v8, vcc
	v_or_b32_e32 v8, 16, v9
	v_cmp_gt_i32_e32 vcc, v8, v29
	v_mov_b32_e32 v8, s41
	v_or_b32_e32 v18, s12, v30
	v_cndmask_b32_e32 v4, v4, v8, vcc
	v_cmp_lt_i32_e32 vcc, v9, v29
	v_or_b32_e32 v8, 17, v9
	s_movk_i32 s9, 0x90
	v_cndmask_b32_e32 v0, v11, v0, vcc
	v_cndmask_b32_e32 v1, 0, v1, vcc
	v_cmp_le_i32_e32 vcc, v8, v29
	v_or_b32_e32 v8, 2, v9
	v_cvt_pk_bf16_f32 v0, v0, v1
	v_mad_u64_u32 v[24:25], s[0:1], v18, s9, v[26:27]
	v_cndmask_b32_e32 v5, 0, v5, vcc
	v_cmp_le_i32_e32 vcc, v8, v29
	v_or_b32_e32 v8, 18, v9
	v_mad_u32_u24 v19, v30, s9, v26
	v_cndmask_b32_e32 v2, 0, v2, vcc
	v_cmp_le_i32_e32 vcc, v8, v29
	v_or_b32_e32 v8, 3, v9
	s_nop 0
	v_cndmask_b32_e32 v6, 0, v6, vcc
	v_cmp_le_i32_e32 vcc, v8, v29
	v_or_b32_e32 v8, 19, v9
	s_nop 0
	v_cndmask_b32_e32 v3, 0, v3, vcc
	v_cmp_le_i32_e32 vcc, v8, v29
	v_cvt_pk_bf16_f32 v1, v2, v3
	ds_write_b64 v10, v[0:1] offset:46080
	v_cvt_pk_bf16_f32 v0, v4, v5
	s_nop 0
	v_cndmask_b32_e32 v7, 0, v7, vcc
	v_cvt_pk_bf16_f32 v1, v6, v7
	ds_write_b64 v10, v[0:1] offset:46112
	s_waitcnt vmcnt(0)
	s_nop 0
	s_waitcnt lgkmcnt(0)
	s_barrier
	ds_read_b128 v[36:39], v24 offset:27648
	ds_read_b128 v[186:189], v19 offset:46080
	ds_read_b128 v[190:193], v19 offset:48384
	ds_read_b128 v[194:197], v19 offset:50688
	ds_read_b128 v[206:209], v19 offset:52992
	ds_read_b128 v[218:221], v24 offset:27712
	ds_read_b128 v[222:225], v19 offset:46144
	ds_read_b128 v[226:229], v19 offset:53056
	ds_read_b128 v[230:233], v19 offset:48448
	ds_read_b128 v[234:237], v19 offset:50752
	s_nop 6
	s_waitcnt lgkmcnt(6)
	v_mfma_f32_16x16x32_bf16 v[32:35], v[36:39], v[194:197], 0
	s_nop 0
	s_and_b64 vcc, exec, s[10:11]
	v_mfma_f32_16x16x32_bf16 v[4:7], v[36:39], v[186:189], 0
	v_mfma_f32_16x16x32_bf16 v[8:11], v[36:39], v[190:193], 0
	s_nop 0
	s_waitcnt lgkmcnt(5)
	v_mfma_f32_16x16x32_bf16 v[0:3], v[36:39], v[206:209], 0
	s_nop 1
	s_waitcnt lgkmcnt(3)
	v_mfma_f32_16x16x32_bf16 v[12:15], v[218:221], v[222:225], v[4:7]
	s_nop 4
	s_waitcnt lgkmcnt(1)
	v_mfma_f32_16x16x32_bf16 v[8:11], v[218:221], v[230:233], v[8:11]
	s_nop 0
	s_waitcnt vmcnt(0)
	s_nop 0
	s_waitcnt lgkmcnt(0)
	v_mfma_f32_16x16x32_bf16 v[4:7], v[218:221], v[234:237], v[32:35]
	s_barrier
	v_mfma_f32_16x16x32_bf16 v[0:3], v[218:221], v[226:229], v[0:3]
	s_cbranch_vccnz .LBB0_1258
	s_ashr_i32 s9, s8, 31
	s_lshl_b64 s[0:1], s[8:9], 19
	v_readlane_b32 s8, v254, 8
	s_add_u32 s0, s8, s0
	v_readlane_b32 s8, v254, 11
	v_ashrrev_i32_e32 v19, 31, v18
	s_addc_u32 s1, s8, s1
	v_lshlrev_b64 v[18:19], 7, v[18:19]
	v_lshl_add_u64 v[18:19], s[0:1], 0, v[18:19]
	v_lshlrev_b32_e32 v16, 1, v16
	v_lshl_add_u64 v[18:19], v[18:19], 0, v[16:17]
	global_load_dwordx4 v[22:25], v[18:19], off
	s_nop 0
	global_load_dwordx4 v[18:21], v[18:19], off offset:64
	v_mul_u32_u24_e32 v16, 0x90, v30
	s_mov_b32 s8, 0
	s_mov_b64 s[0:1], -1

; #define LAS __attribute__((address_space(3)))
; template <int TY> __device__ __forceinline__ void mc_item(const Params& p, ldsp lds, int item) {
;     constexpr int DK = TY == 0 ? 64 : (TY == 1 ? 128 : 256), DV = TY == 2 ? 512 : 128, NB = TY == 2 ? 4 : 1, ET = DV / 128, PQ = DK + 8;
;     constexpr int szQ = 64 * PQ * 2, o_qh = szQ, o_kt = (TY == 2 ? 1 : 2) * szQ, o_vt = o_kt + szQ, o_pm = o_vt + DV * 144, o_red = o_pm + 64 * 144;
;     static_assert(o_red + 2048 <= LDS_BYTES, "mc LDS");
;     const int tid = otid(), lane = tid & 63, wave = __builtin_amdgcn_readfirstlane(tid >> 6), l15 = lane & 15, q4 = lane >> 4;
;     const int bh = item >> 5, c = item & 31, b = bh >> 2, h = bh & 3, sc = c / NB, jc = c % NB, row0 = b * 2048 + c * 64;
;     ...
;     if (TY != 2) lds += LDSSHIFT;
;     ...
;     ldsp QX = lds, QH2 = lds + o_qh, KTs = lds + o_kt, VTs = lds + o_vt, Pm = lds + o_pm; LAS float* RED = (LAS float*)(lds + o_red);
;     const bf16_t* Pb = (const bf16_t*)(p.ws + WS_P);
;     constexpr int PP = TY == 2 ? NO : NE;
;     const int ecol = TY ? 256 + h * 128 : h * 64;
;     if (TY == 2) stage_rows<DK>(QX, PQ, Pb + (size_t)row0 * NO + O_Q + h * 256, NO, tid);
;     else { stage_rows<DK>(QX, PQ, (const bf16_t*)(p.ws + WS_QT) + (size_t)row0 * 768 + ecol, 768, tid);
;            stage_rows<DK>(QH2, PQ, (const bf16_t*)(p.ws + WS_QH) + (size_t)row0 * 768 + ecol, 768, tid); }
;     f32x4 acc[ET][4];
; #pragma unroll
;     for (int ei = 0; ei < ET; ++ei)
; #pragma unroll
;         for (int tk = 0; tk < 4; ++tk) acc[ei][tk] = (f32x4){0.f, 0.f, 0.f, 0.f};
;     const int voff = TY == 0 ? E_VA + h * 128 : (TY == 1 ? E_IB + h * 128 : O_V + h * 512);
;     const int tt = wave & 3, sp = wave >> 2;
;     u32x4 kr[TY == 2 ? 4 : 1], vr[TY == 2 ? 8 : 1];
;     if constexpr (TY == 2) { const size_t rowq = (size_t)b * 2048 + (sc * NB) * 64;
;         ld_rows<256>(kr, Pb + rowq * NO + O_K + h * 256, NO, tid); ld_T<512>(vr, Pb + rowq * NO + voff, NO, wave, lane); }
;     for (int j = 0; j <= jc; ++j) { const size_t rowj = (size_t)b * 2048 + (sc * NB + j) * 64;
;         if constexpr (TY == 2) { st_rows<256>(KTs, PQ, kr, tid); st_T<512>(VTs, 72, vr, wave, lane); }
;         else { stage_rows<DK>(KTs, PQ, (const bf16_t*)(p.ws + WS_KT) + rowj * 768 + ecol, 768, tid);
;                stage_T<DV>(VTs, 72, Pb + rowj * PP + voff, PP, wave, lane); }
.LBB0_1270:
	s_add_i32 s12, s8, 0xfffffc00
	s_and_b32 s1, s8, 31
	s_lshr_b32 s40, s12, 7
	s_lshl_b32 s9, s40, 11
	s_lshl_b32 s11, s1, 6
	s_or_b32 s9, s9, s11
	s_lshl_b32 s10, s12, 2
	v_mov_b32_e32 v22, v161
	s_and_b32 s10, s10, 0x180
	s_mul_i32 s16, s9, 0x600
	s_mul_hi_u32 s13, s9, 0x600
	s_add_u32 s14, s28, s16
	v_add_u32_e32 v6, 0x200, v22
	s_addc_u32 s15, s29, s13
	s_lshl_b32 s10, s10, 1
	v_ashrrev_i32_e32 v0, 31, v22
	v_ashrrev_i32_e32 v7, 31, v6
	s_add_u32 s14, s14, s10
	v_lshrrev_b32_e32 v0, 28, v0
	v_lshrrev_b32_e32 v7, 28, v7
	s_addc_u32 s15, s15, 0
	v_add_u32_e32 v0, v22, v0
	v_add_u32_e32 v7, v6, v7
	v_ashrrev_i32_e32 v40, 4, v0
	v_and_b32_e32 v0, 0x1ffffff0, v0
	v_mov_b64_e32 v[4:5], s[14:15]
	v_ashrrev_i32_e32 v41, 4, v7
	v_sub_u32_e32 v2, v22, v0
	v_mad_i64_i32 v[0:1], s[14:15], v40, s60, v[4:5]
	v_mad_i64_i32 v[4:5], s[14:15], v41, s60, v[4:5]
	s_add_u32 s14, s22, s16
	s_addc_u32 s13, s23, s13
	s_add_u32 s14, s14, s10
	s_addc_u32 s15, s13, 0
	v_mov_b64_e32 v[12:13], s[14:15]
	v_mad_i64_i32 v[8:9], s[14:15], v40, s60, v[12:13]
	v_mad_i64_i32 v[12:13], s[14:15], v41, s60, v[12:13]
	s_lshl_b64 s[14:15], s[40:41], 11
	s_or_b32 s11, s14, s11
	s_mul_hi_u32 s14, s11, 0x600
	s_mul_i32 s17, s15, 0x600
	v_readfirstlane_b32 s0, v22
	s_mul_i32 s16, s11, 0x600
	s_add_i32 s17, s14, s17
	s_mul_i32 s14, s11, 0x1e00
	s_mul_hi_u32 s11, s11, 0x1e00
	s_mulk_i32 s15, 0x1e00
	s_ashr_i32 s13, s0, 6
	s_add_i32 s11, s11, s15
	v_and_b32_e32 v7, 0x1ffffff0, v7
	s_add_u32 s14, s26, s14
	v_sub_u32_e32 v6, v6, v7
	s_addc_u32 s11, s27, s11
	v_lshlrev_b32_e32 v38, 3, v6
	s_add_u32 s14, s14, s10
	v_ashrrev_i32_e32 v39, 31, v38
	s_addc_u32 s15, s11, 0
	s_lshl_b32 s11, s13, 5
	v_and_b32_e32 v16, 31, v22
	v_lshlrev_b64 v[24:25], 1, v[38:39]
	v_and_or_b32 v39, s11, 32, v16
	v_mul_u32_u24_e32 v16, 0xf00, v39
	v_lshlrev_b32_e32 v16, 1, v16
	v_lshlrev_b32_e32 v36, 3, v2
	v_lshl_add_u64 v[20:21], s[14:15], 0, v[16:17]
	v_bfe_u32 v16, v22, 5, 1
	v_ashrrev_i32_e32 v37, 31, v36
	v_and_or_b32 v16, s13, -2, v16
	s_lshl_b32 s11, s13, 4
	s_ashr_i32 s13, s0, 3
	v_lshlrev_b64 v[18:19], 1, v[36:37]
	s_andn2_b32 s13, s13, 31
	v_lshl_add_u64 v[0:1], v[0:1], 0, v[18:19]
	s_add_u32 s14, s72, s16
	global_load_dwordx4 v[0:3], v[0:1], off offset:512
	s_addc_u32 s15, s73, s17
	v_lshlrev_b32_e32 v26, 3, v16
	s_add_u32 s14, s14, s10
	v_lshl_add_u64 v[4:5], v[4:5], 0, v[24:25]
	v_ashrrev_i32_e32 v27, 31, v26
	s_addc_u32 s15, s15, 0
	global_load_dwordx4 v[4:7], v[4:5], off offset:512
	v_lshl_add_u64 v[8:9], v[8:9], 0, v[18:19]
	v_lshl_add_u64 v[32:33], v[26:27], 1, v[20:21]
	v_mov_b64_e32 v[26:27], s[14:15]
	global_load_dwordx4 v[8:11], v[8:9], off offset:512
	v_lshl_add_u64 v[12:13], v[12:13], 0, v[24:25]
	v_mad_i64_i32 v[20:21], s[14:15], v40, s60, v[26:27]
	global_load_dwordx4 v[12:15], v[12:13], off offset:512
	v_lshl_add_u64 v[18:19], v[20:21], 0, v[18:19]
	v_mad_i64_i32 v[26:27], s[14:15], v41, s60, v[26:27]
	global_load_dwordx4 v[18:21], v[18:19], off offset:512
	v_lshl_add_u64 v[24:25], v[26:27], 0, v[24:25]
	v_add_co_u32_e32 v28, vcc, s57, v32
	global_load_dwordx4 v[24:27], v[24:25], off offset:512
	s_nop 0
	v_addc_co_u32_e32 v29, vcc, 0, v33, vcc
	global_load_dwordx4 v[28:31], v[28:29], off offset:1024
	s_mov_b64 s[14:15], 0x1400
	v_lshl_add_u64 v[32:33], v[32:33], 0, s[14:15]
	global_load_dwordx4 v[32:35], v[32:33], off offset:128
	s_movk_i32 s16, 0x88
	v_mad_u64_u32 v[36:37], s[14:15], v40, s16, v[36:37]
	v_lshl_add_u32 v36, v36, 1, 0
	v_and_b32_e32 v23, 15, v22
	s_cmp_eq_u32 s1, 0
	s_waitcnt vmcnt(0)
	ds_write_b128 v36, v[0:3]
	v_mad_u64_u32 v[0:1], s[14:15], v41, s16, v[38:39]
	s_movk_i32 s14, 0x240
	v_lshl_add_u32 v2, v0, 1, 0
	v_mul_lo_u32 v0, v16, s14
	ds_write_b128 v2, v[4:7]
	ds_write_b128 v36, v[8:11] offset:17408
	ds_write_b128 v2, v[12:15] offset:17408
	v_bfe_u32 v9, v22, 4, 2
	v_or_b32_e32 v0, v39, v0
	v_lshl_add_u32 v3, v0, 1, 0
	v_lshlrev_b32_e32 v8, 3, v9
	v_or_b32_e32 v0, s13, v23
	v_mad_u64_u32 v[0:1], s[14:15], v0, s16, v[8:9]
	ds_write_b128 v36, v[18:21] offset:34816
	ds_write_b128 v2, v[24:27] offset:34816
	ds_write_b16 v3, v28 offset:52224
	ds_write_b16_d16_hi v3, v28 offset:52368
	ds_write_b16 v3, v29 offset:52512
	ds_write_b16_d16_hi v3, v29 offset:52656
	ds_write_b16 v3, v30 offset:52800
	ds_write_b16_d16_hi v3, v30 offset:52944
	ds_write_b16 v3, v31 offset:53088
	ds_write_b16_d16_hi v3, v31 offset:53232
	ds_write_b16 v3, v32 offset:61440
	ds_write_b16_d16_hi v3, v32 offset:61584
	ds_write_b16 v3, v33 offset:61728
	ds_write_b16_d16_hi v3, v33 offset:61872
	ds_write_b16 v3, v34 offset:62016
	ds_write_b16_d16_hi v3, v34 offset:62160
	ds_write_b16 v3, v35 offset:62304
	ds_write_b16_d16_hi v3, v35 offset:62448
	v_lshl_add_u32 v14, v0, 1, 0
	s_waitcnt vmcnt(0) lgkmcnt(0)
	s_nop 0
	s_barrier
; #define LAS __attribute__((address_space(3)))
; __device__ __forceinline__ unsigned pk2(float lo, float hi) { return pg8::cvt_pk_bf16(lo, hi); }
; __device__ __forceinline__ f32x4 mma16(bf16x8 a, bf16x8 b, f32x4 c) { return __builtin_amdgcn_mfma_f32_16x16x32_bf16(a, b, c, 0, 0, 0); }
; template <int TY> __device__ __forceinline__ void mc_item(const Params& p, ldsp lds, int item) {
;     ...
;         { f32x4 c0 = (f32x4){0.f, 0.f, 0.f, 0.f}, c1 = c0;
; #pragma unroll
;           for (int ks = 0; ks < DK / 32; ++ks) { const bf16x8 bq = ldfrag(QX, (16 * tt + l15) * PQ + 32 * ks + 8 * q4);
;               c0 = mma16(ldfrag(KTs, (16 * (2 * sp) + l15) * PQ + 32 * ks + 8 * q4), bq, c0);
;               c1 = mma16(ldfrag(KTs, (16 * (2 * sp + 1) + l15) * PQ + 32 * ks + 8 * q4), bq, c1); }
;           const int t = 16 * tt + l15;
;           const int tl = (j == jc) ? t : 4096;
; #pragma unroll
;           for (int jj = 0; jj < 4; ++jj) { if (32 * sp + 4 * q4 + jj > tl) c0[jj] = 0.f; if (32 * sp + 16 + 4 * q4 + jj > tl) c1[jj] = 0.f; }
;           u32x2 w; w.x = pk2(c0[0], c0[1]); w.y = pk2(c0[2], c0[3]); *(LAS u32x2*)(Pm + (size_t)(t * 72 + 32 * sp + 4 * q4) * 2) = w;
;           w.x = pk2(c1[0], c1[1]); w.y = pk2(c1[2], c1[3]); *(LAS u32x2*)(Pm + (size_t)(t * 72 + 32 * sp + 16 + 4 * q4) * 2) = w; }
;         if constexpr (TY == 2) __syncthreads(); else BSYNC();
; #pragma unroll
;         for (int ks = 0; ks < 2; ++ks) { bf16x8 pb[4];
; #pragma unroll
;             for (int tk = 0; tk < 4; ++tk) pb[tk] = ldfrag(Pm, (16 * tk + l15) * 72 + 32 * ks + 8 * q4);
; #pragma unroll
;             for (int ei = 0; ei < ET; ++ei) { const bf16x8 va = ldfrag(VTs, (16 * (wave * ET + ei) + l15) * 72 + 32 * ks + 8 * q4);
; #pragma unroll
;                 for (int tk = 0; tk < 4; ++tk) acc[ei][tk] = mma16(va, pb[tk], acc[ei][tk]); } }
;         if constexpr (TY == 2) __syncthreads(); else BSYNC(); }
;     if ((TY == 2 ? sc : c) != 0) { const bf16_t* STp = (TY == 2) ? (const bf16_t*)(p.ws + WS_ST) + ((size_t)bh * 8 + sc) * 512 * 256
;                                     : (const bf16_t*)(p.ws + WS_ST + (TY ? ST_HGRN : 0)) + ((size_t)bh * 32 + c) * 128 * DK;
;       ldsp QS = (TY == 2) ? QX : QH2;
;       bf16x8 sa[ET], sn[ET];
; #pragma unroll
;       for (int ei = 0; ei < ET; ++ei) sa[ei] = *(const bf16x8*)(STp + (size_t)(16 * (wave * ET + ei) + l15) * DK + 8 * q4);
	ds_read_b128 v[26:29], v14 offset:34816
	s_nop 0
	v_and_or_b32 v15, s11, 48, v23
	v_mad_u32_u24 v4, v15, s16, v8
	v_lshl_add_u32 v16, v4, 1, 0
	ds_read_b128 v[34:37], v16
	ds_read_b128 v[186:189], v14 offset:39168
	ds_read_b128 v[190:193], v14 offset:34880
	ds_read_b128 v[194:197], v16 offset:64
	ds_read_b128 v[206:209], v14 offset:39232
	ds_read_b128 v[218:221], v14 offset:34944
	ds_read_b128 v[222:225], v16 offset:128
	ds_read_b128 v[226:229], v14 offset:39296
	ds_read_b128 v[230:233], v14 offset:35008
	ds_read_b128 v[234:237], v16 offset:192
	ds_read_b128 v[238:241], v14 offset:39360
	s_nop 3
	s_waitcnt lgkmcnt(10)
	v_mfma_f32_16x16x32_bf16 v[0:3], v[26:29], v[34:37], 0
	v_readlane_b32 s14, v255, 24
	s_nop 0
	s_waitcnt lgkmcnt(9)
	v_mfma_f32_16x16x32_bf16 v[4:7], v[186:189], v[34:37], 0
	s_nop 2
	s_waitcnt lgkmcnt(7)
	v_mfma_f32_16x16x32_bf16 v[0:3], v[190:193], v[194:197], v[0:3]
	s_nop 1
	s_waitcnt lgkmcnt(6)
	v_mfma_f32_16x16x32_bf16 v[4:7], v[206:209], v[194:197], v[4:7]
	s_nop 0
	v_lshlrev_b32_e32 v24, 2, v9
	v_or_b32_e32 v9, s13, v24
	s_nop 0
	s_waitcnt lgkmcnt(4)
	v_mfma_f32_16x16x32_bf16 v[0:3], v[218:221], v[222:225], v[0:3]
	s_nop 1
	v_cmp_gt_i32_e32 vcc, v9, v15
	s_movk_i32 s13, 0x90
	s_nop 0
	s_waitcnt lgkmcnt(3)
	v_mfma_f32_16x16x32_bf16 v[4:7], v[226:229], v[222:225], v[4:7]
	s_nop 1
	v_mad_u32_u24 v14, v15, s53, v9
	v_lshl_add_u32 v14, v14, 1, s14
	s_nop 0
	s_waitcnt lgkmcnt(1)
	v_mfma_f32_16x16x32_bf16 v[0:3], v[230:233], v[234:237], v[0:3]
	v_and_b32_e32 v25, 48, v22
	s_nop 0
	s_waitcnt lgkmcnt(0)
	v_mfma_f32_16x16x32_bf16 v[4:7], v[238:241], v[234:237], v[4:7]
	v_mov_b32_e32 v12, s41
	s_nop 3
	v_cndmask_b32_e32 v13, v0, v12, vcc
	v_or_b32_e32 v12, 16, v9
	v_cmp_gt_i32_e32 vcc, v12, v15
	v_mov_b32_e32 v12, s41
	v_or_b32_e32 v10, s11, v23
	v_cndmask_b32_e32 v4, v4, v12, vcc
	v_cmp_lt_i32_e32 vcc, v9, v15
	v_or_b32_e32 v12, 17, v9
	v_mul_lo_u32 v11, v10, s13
	v_cndmask_b32_e32 v0, v13, v0, vcc
	v_cndmask_b32_e32 v1, 0, v1, vcc
	v_cmp_le_i32_e32 vcc, v12, v15
	v_or_b32_e32 v12, 2, v9
	v_cvt_pk_bf16_f32 v0, v0, v1
	s_nop 0
	v_cndmask_b32_e32 v5, 0, v5, vcc
	v_cmp_le_i32_e32 vcc, v12, v15
	v_or_b32_e32 v12, 18, v9
	s_nop 0
	v_cndmask_b32_e32 v2, 0, v2, vcc
	v_cmp_le_i32_e32 vcc, v12, v15
	v_or_b32_e32 v12, 3, v9
	v_or_b32_e32 v9, 19, v9
	v_cndmask_b32_e32 v6, 0, v6, vcc
	v_cmp_le_i32_e32 vcc, v12, v15
	s_nop 1
	v_cndmask_b32_e32 v3, 0, v3, vcc
	v_cmp_le_i32_e32 vcc, v9, v15
	v_cvt_pk_bf16_f32 v1, v2, v3
	v_add3_u32 v9, 0, v25, v11
	ds_write_b64 v14, v[0:1]
	v_cndmask_b32_e32 v7, 0, v7, vcc
	v_cvt_pk_bf16_f32 v0, v4, v5
	v_cvt_pk_bf16_f32 v1, v6, v7
	ds_write_b64 v14, v[0:1] offset:32
	s_waitcnt vmcnt(0)
	s_nop 0
	s_waitcnt lgkmcnt(0)
	s_barrier
	ds_read_b128 v[26:29], v9 offset:52224
	s_nop 0
	v_mul_u32_u24_e32 v4, 0x90, v23
	v_add3_u32 v11, s14, v25, v4
	ds_read_b128 v[34:37], v11
	ds_read_b128 v[186:189], v11 offset:2304
	ds_read_b128 v[190:193], v11 offset:4608
	ds_read_b128 v[194:197], v11 offset:6912
	ds_read_b128 v[206:209], v9 offset:52288
	ds_read_b128 v[218:221], v11 offset:64
	ds_read_b128 v[222:225], v11 offset:2368
	ds_read_b128 v[226:229], v11 offset:6976
	ds_read_b128 v[230:233], v11 offset:4672
	s_nop 5
	s_waitcnt lgkmcnt(6)
	v_mfma_f32_16x16x32_bf16 v[30:33], v[26:29], v[190:193], 0
	s_nop 0
	v_mfma_f32_16x16x32_bf16 v[4:7], v[26:29], v[34:37], 0
	s_nop 0
	s_waitcnt lgkmcnt(3)
	v_mfma_f32_16x16x32_bf16 v[18:21], v[206:209], v[218:221], v[4:7]
	v_mfma_f32_16x16x32_bf16 v[12:15], v[26:29], v[186:189], 0
	s_nop 5
	v_mfma_f32_16x16x32_bf16 v[0:3], v[26:29], v[194:197], 0
	s_nop 1
	s_waitcnt lgkmcnt(2)
	v_mfma_f32_16x16x32_bf16 v[12:15], v[206:209], v[222:225], v[12:15]
	s_nop 0
	s_waitcnt vmcnt(0)
	s_nop 0
	s_waitcnt lgkmcnt(0)
	v_mfma_f32_16x16x32_bf16 v[4:7], v[206:209], v[230:233], v[30:33]
	s_barrier
	v_mfma_f32_16x16x32_bf16 v[0:3], v[206:209], v[226:229], v[0:3]
	s_cbranch_scc1 .LBB0_1273
	s_lshr_b32 s40, s12, 5
	s_lshl_b64 s[12:13], s[40:41], 20
	v_readlane_b32 s14, v254, 4
	s_add_u32 s12, s14, s12
	v_readlane_b32 s14, v254, 6
	s_addc_u32 s13, s14, s13
	s_lshl_b32 s1, s1, 15
	s_add_u32 s12, s12, s1
	v_ashrrev_i32_e32 v11, 31, v10
	s_addc_u32 s13, s13, 0
	v_lshlrev_b64 v[10:11], 8, v[10:11]
	v_lshl_add_u64 v[10:11], s[12:13], 0, v[10:11]
	v_lshlrev_b32_e32 v16, 1, v8
	v_lshl_add_u64 v[8:9], v[10:11], 0, v[16:17]
	v_mul_u32_u24_e32 v10, 0x110, v23
	s_add_i32 s1, 0, 0x4400
	v_add3_u32 v16, v10, v25, s1
	s_mov_b32 s1, 32
	v_mov_b64_e32 v[10:11], v[8:9]

; #define LAS __attribute__((address_space(3)))
; #define BSYNC() do { asm volatile("s_waitcnt vmcnt(0) lgkmcnt(0)" ::: "memory"); __syncthreads(); } while (0)
; template <int TY> __device__ __forceinline__ void mc_item(const Params& p, ldsp lds, int item) {
;     ...
;     const int bh = item >> 5, c = item & 31, b = bh >> 2, h = bh & 3, sc = c / NB, jc = c % NB, row0 = b * 2048 + c * 64;
;     ...
;     if (TY != 2) lds += LDSSHIFT;
;     ...
;     ldsp QX = lds, QH2 = lds + o_qh, KTs = lds + o_kt, VTs = lds + o_vt, Pm = lds + o_pm; LAS float* RED = (LAS float*)(lds + o_red);
;     const bf16_t* Pb = (const bf16_t*)(p.ws + WS_P);
;     constexpr int PP = TY == 2 ? NO : NE;
;     const int ecol = TY ? 256 + h * 128 : h * 64;
;     if (TY == 2) stage_rows<DK>(QX, PQ, Pb + (size_t)row0 * NO + O_Q + h * 256, NO, tid);
;     else { stage_rows<DK>(QX, PQ, (const bf16_t*)(p.ws + WS_QT) + (size_t)row0 * 768 + ecol, 768, tid);
;            stage_rows<DK>(QH2, PQ, (const bf16_t*)(p.ws + WS_QH) + (size_t)row0 * 768 + ecol, 768, tid); }
;     f32x4 acc[ET][4];
; #pragma unroll
;     for (int ei = 0; ei < ET; ++ei)
; #pragma unroll
;         for (int tk = 0; tk < 4; ++tk) acc[ei][tk] = (f32x4){0.f, 0.f, 0.f, 0.f};
;     const int voff = TY == 0 ? E_VA + h * 128 : (TY == 1 ? E_IB + h * 128 : O_V + h * 512);
;     const int tt = wave & 3, sp = wave >> 2;
;     u32x4 kr[TY == 2 ? 4 : 1], vr[TY == 2 ? 8 : 1];
;     if constexpr (TY == 2) { const size_t rowq = (size_t)b * 2048 + (sc * NB) * 64;
;         ld_rows<256>(kr, Pb + rowq * NO + O_K + h * 256, NO, tid); ld_T<512>(vr, Pb + rowq * NO + voff, NO, wave, lane); }
;     for (int j = 0; j <= jc; ++j) { const size_t rowj = (size_t)b * 2048 + (sc * NB + j) * 64;
;         if constexpr (TY == 2) { st_rows<256>(KTs, PQ, kr, tid); st_T<512>(VTs, 72, vr, wave, lane); }
;         else { stage_rows<DK>(KTs, PQ, (const bf16_t*)(p.ws + WS_KT) + rowj * 768 + ecol, 768, tid);
;                stage_T<DV>(VTs, 72, Pb + rowj * PP + voff, PP, wave, lane); }
;         if constexpr (TY == 2) { __syncthreads(); if (j < jc) { const size_t rown = rowj + 64; ld_rows<256>(kr, Pb + rown * NO + O_K + h * 256, NO, tid); ld_T<512>(vr, Pb + rown * NO + voff, NO, wave, lane); } }
;         else BSYNC();
.LBB0_1282:
	s_and_b32 s13, s8, 31
	s_ashr_i32 s14, s8, 7
	s_lshl_b32 s9, s14, 11
	s_lshl_b32 s10, s13, 6
	s_ashr_i32 s0, s8, 5
	s_or_b32 s11, s9, s10
	v_mov_b32_e32 v27, v161
	s_and_b32 s1, s0, 3
	s_mul_i32 s18, s11, 0x600
	s_mul_hi_i32 s15, s11, 0x600
	s_add_u32 s16, s28, s18
	v_ashrrev_i32_e32 v0, 31, v27
	s_addc_u32 s17, s29, s15
	s_lshl_b32 s9, s1, 7
	v_lshrrev_b32_e32 v0, 29, v0
	s_add_u32 s16, s16, s9
	v_add_u32_e32 v0, v27, v0
	s_addc_u32 s17, s17, 0
	v_ashrrev_i32_e32 v24, 3, v0
	v_and_b32_e32 v0, 0x1ffffff8, v0
	v_sub_u32_e32 v2, v27, v0
	v_mov_b64_e32 v[0:1], s[16:17]
	v_mad_i64_i32 v[0:1], s[16:17], v24, s60, v[0:1]
	s_add_u32 s16, s22, s18
	s_addc_u32 s15, s23, s15
	s_add_u32 s16, s16, s9
	s_addc_u32 s17, s15, 0
	s_ashr_i32 s15, s14, 31
	v_mov_b64_e32 v[4:5], s[16:17]
	s_lshl_b64 s[14:15], s[14:15], 11
	v_mad_i64_i32 v[4:5], s[16:17], v24, s60, v[4:5]
	s_or_b32 s10, s14, s10
	s_mul_i32 s14, s15, 0x600
	s_mul_hi_u32 s17, s10, 0x600
	v_readfirstlane_b32 s12, v27
	s_add_i32 s17, s17, s14
	s_mul_i32 s14, s15, 0x1e00
	s_mul_hi_u32 s15, s10, 0x1e00
	s_ashr_i32 s16, s12, 6
	s_mul_i32 s18, s10, 0x600
	s_add_i32 s15, s15, s14
	s_mulk_i32 s10, 0x1e00
	s_add_u32 s10, s26, s10
	s_addc_u32 s15, s27, s15
	s_lshl_b32 s1, s1, 8
	s_add_u32 s14, s10, s1
	s_addc_u32 s15, s15, 0
	s_lshl_b32 s1, s16, 5
	v_and_b32_e32 v10, 31, v27
	v_and_or_b32 v25, s1, 32, v10
	v_mul_u32_u24_e32 v10, 0xf00, v25
	s_ashr_i32 s1, s12, 3
	v_lshlrev_b32_e32 v16, 1, v10
	s_lshl_b32 s10, s16, 4
	s_andn2_b32 s1, s1, 31
	v_lshl_add_u64 v[10:11], s[14:15], 0, v[16:17]
	v_bfe_u32 v12, v27, 5, 1
	s_add_u32 s14, s72, s18
	v_and_or_b32 v26, s16, -2, v12
	s_addc_u32 s15, s73, s17
	v_lshlrev_b32_e32 v12, 3, v26
	s_add_u32 s14, s14, s9
	v_lshlrev_b32_e32 v22, 3, v2
	v_ashrrev_i32_e32 v13, 31, v12
	s_addc_u32 s15, s15, 0
	v_ashrrev_i32_e32 v23, 31, v22
	v_lshl_add_u64 v[18:19], v[12:13], 1, v[10:11]
	v_mov_b64_e32 v[10:11], s[14:15]
	v_lshlrev_b64 v[8:9], 1, v[22:23]
	v_mad_i64_i32 v[10:11], s[14:15], v24, s60, v[10:11]
	v_lshl_add_u64 v[0:1], v[0:1], 0, v[8:9]
	v_lshl_add_u64 v[4:5], v[4:5], 0, v[8:9]
	v_lshl_add_u64 v[8:9], v[10:11], 0, v[8:9]
	global_load_dwordx4 v[0:3], v[0:1], off
	v_mad_u64_u32 v[22:23], s[14:15], v24, s53, v[22:23]
	global_load_dwordx4 v[4:7], v[4:5], off
	s_nop 0
	global_load_dwordx4 v[8:11], v[8:9], off
	s_nop 0
	global_load_dwordx4 v[12:15], v[18:19], off offset:1024
	s_nop 0
	global_load_dwordx4 v[18:21], v[18:19], off offset:1152
	s_movk_i32 s14, 0x240
	v_and_b32_e32 v30, 15, v27
	v_bfe_u32 v28, v27, 4, 2
	v_lshl_add_u32 v24, v22, 1, 0
	v_mul_lo_u32 v22, v26, s14
	v_lshlrev_b32_e32 v16, 3, v28
	v_or_b32_e32 v22, v25, v22
	v_or_b32_e32 v23, s1, v30
	v_lshl_add_u32 v25, v22, 1, 0
	v_mad_u64_u32 v[22:23], s[14:15], v23, s53, v[16:17]
	v_lshl_add_u32 v22, v22, 1, 0
	v_and_or_b32 v29, s10, 48, v30
	v_lshlrev_b32_e32 v28, 2, v28
	s_cmp_eq_u32 s13, 0
	s_waitcnt vmcnt(0)
	ds_write_b128 v24, v[0:3]
	ds_write_b128 v24, v[4:7] offset:9216
	ds_write_b128 v24, v[8:11] offset:18432
	ds_write_b16 v25, v12 offset:27648
	ds_write_b16_d16_hi v25, v12 offset:27792
	ds_write_b16 v25, v13 offset:27936
	ds_write_b16_d16_hi v25, v13 offset:28080
	ds_write_b16 v25, v14 offset:28224
	ds_write_b16_d16_hi v25, v14 offset:28368
	ds_write_b16 v25, v15 offset:28512
	ds_write_b16_d16_hi v25, v15 offset:28656
	ds_write_b16 v25, v18 offset:36864
	ds_write_b16_d16_hi v25, v18 offset:37008
	ds_write_b16 v25, v19 offset:37152
	ds_write_b16_d16_hi v25, v19 offset:37296
	ds_write_b16 v25, v20 offset:37440
	ds_write_b16_d16_hi v25, v20 offset:37584
	ds_write_b16 v25, v21 offset:37728
	ds_write_b16_d16_hi v25, v21 offset:37872
	s_waitcnt vmcnt(0) lgkmcnt(0)
	s_nop 0
	s_barrier
; template <int TY> __device__ __forceinline__ void mc_item(const Params& p, ldsp lds, int item) {
;     ...
;         { f32x4 c0 = (f32x4){0.f, 0.f, 0.f, 0.f}, c1 = c0;
; #pragma unroll
;           for (int ks = 0; ks < DK / 32; ++ks) { const bf16x8 bq = ldfrag(QX, (16 * tt + l15) * PQ + 32 * ks + 8 * q4);
;               c0 = mma16(ldfrag(KTs, (16 * (2 * sp) + l15) * PQ + 32 * ks + 8 * q4), bq, c0);
;               c1 = mma16(ldfrag(KTs, (16 * (2 * sp + 1) + l15) * PQ + 32 * ks + 8 * q4), bq, c1); }
;           const int t = 16 * tt + l15;
;           const int tl = (j == jc) ? t : 4096;
; #pragma unroll
;           for (int jj = 0; jj < 4; ++jj) { if (32 * sp + 4 * q4 + jj > tl) c0[jj] = 0.f; if (32 * sp + 16 + 4 * q4 + jj > tl) c1[jj] = 0.f; }
;           u32x2 w; w.x = pk2(c0[0], c0[1]); w.y = pk2(c0[2], c0[3]); *(LAS u32x2*)(Pm + (size_t)(t * 72 + 32 * sp + 4 * q4) * 2) = w;
;           w.x = pk2(c1[0], c1[1]); w.y = pk2(c1[2], c1[3]); *(LAS u32x2*)(Pm + (size_t)(t * 72 + 32 * sp + 16 + 4 * q4) * 2) = w; }
;         if constexpr (TY == 2) __syncthreads(); else BSYNC();
; #pragma unroll
;         for (int ks = 0; ks < 2; ++ks) { bf16x8 pb[4];
; #pragma unroll
;             for (int tk = 0; tk < 4; ++tk) pb[tk] = ldfrag(Pm, (16 * tk + l15) * 72 + 32 * ks + 8 * q4);
; #pragma unroll
;             for (int ei = 0; ei < ET; ++ei) { const bf16x8 va = ldfrag(VTs, (16 * (wave * ET + ei) + l15) * 72 + 32 * ks + 8 * q4);
; #pragma unroll
;                 for (int tk = 0; tk < 4; ++tk) acc[ei][tk] = mma16(va, pb[tk], acc[ei][tk]); } }
;         if constexpr (TY == 2) __syncthreads(); else BSYNC(); }
;     if ((TY == 2 ? sc : c) != 0) { const bf16_t* STp = (TY == 2) ? (const bf16_t*)(p.ws + WS_ST) + ((size_t)bh * 8 + sc) * 512 * 256
;                                     : (const bf16_t*)(p.ws + WS_ST + (TY ? ST_HGRN : 0)) + ((size_t)bh * 32 + c) * 128 * DK;
;       ldsp QS = (TY == 2) ? QX : QH2;
;       bf16x8 sa[ET], sn[ET];
; #pragma unroll
;       for (int ei = 0; ei < ET; ++ei) sa[ei] = *(const bf16x8*)(STp + (size_t)(16 * (wave * ET + ei) + l15) * DK + 8 * q4);
; #pragma unroll 1
;       for (int ks = 0; ks < DK / 32; ++ks) { bf16x8 qb[4];
;           const int kn = (ks + 1 < DK / 32) ? ks + 1 : ks;
; #pragma unroll
;           for (int ei = 0; ei < ET; ++ei) sn[ei] = *(const bf16x8*)(STp + (size_t)(16 * (wave * ET + ei) + l15) * DK + 32 * kn + 8 * q4);
	ds_read_b128 v[36:39], v22 offset:18432
	s_nop 0
	v_mad_u32_u24 v4, v29, s53, v16
	v_lshl_add_u32 v18, v4, 1, 0
	ds_read_b128 v[186:189], v18
	ds_read_b128 v[190:193], v22 offset:20736
	ds_read_b128 v[194:197], v22 offset:18496
	ds_read_b128 v[206:209], v18 offset:64
	ds_read_b128 v[218:221], v22 offset:20800
	s_nop 2
	s_waitcnt lgkmcnt(4)
	v_mfma_f32_16x16x32_bf16 v[0:3], v[36:39], v[186:189], 0
	s_nop 3
	s_waitcnt lgkmcnt(3)
	v_mfma_f32_16x16x32_bf16 v[4:7], v[190:193], v[186:189], 0
	v_or_b32_e32 v9, s1, v28
	v_mad_u32_u24 v8, v29, s53, v9
	v_lshl_add_u32 v10, v8, 1, 0
	s_nop 0
	s_waitcnt lgkmcnt(1)
	v_mfma_f32_16x16x32_bf16 v[0:3], v[194:197], v[206:209], v[0:3]
	v_and_b32_e32 v8, 48, v27
	v_add_u32_e32 v26, 0, v8
	v_cmp_gt_i32_e32 vcc, v9, v29
	s_nop 0
	s_waitcnt lgkmcnt(0)
	v_mfma_f32_16x16x32_bf16 v[4:7], v[218:221], v[206:209], v[4:7]
	v_mov_b32_e32 v8, s41
	s_nop 1
	v_cndmask_b32_e32 v11, v0, v8, vcc
	v_or_b32_e32 v8, 16, v9
	v_cmp_gt_i32_e32 vcc, v8, v29
	v_mov_b32_e32 v8, s41
	v_or_b32_e32 v18, s10, v30
	v_cndmask_b32_e32 v4, v4, v8, vcc
	v_cmp_lt_i32_e32 vcc, v9, v29
	v_or_b32_e32 v8, 17, v9
	s_movk_i32 s1, 0x90
	v_cndmask_b32_e32 v0, v11, v0, vcc
	v_cndmask_b32_e32 v1, 0, v1, vcc
	v_cmp_le_i32_e32 vcc, v8, v29
	v_or_b32_e32 v8, 2, v9
	v_cvt_pk_bf16_f32 v0, v0, v1
	v_mad_u64_u32 v[24:25], s[14:15], v18, s1, v[26:27]
	v_cndmask_b32_e32 v5, 0, v5, vcc
	v_cmp_le_i32_e32 vcc, v8, v29
	v_or_b32_e32 v8, 18, v9
	v_mad_u32_u24 v19, v30, s1, v26
	v_cndmask_b32_e32 v2, 0, v2, vcc
	v_cmp_le_i32_e32 vcc, v8, v29
	v_or_b32_e32 v8, 3, v9
	s_nop 0
	v_cndmask_b32_e32 v6, 0, v6, vcc
	v_cmp_le_i32_e32 vcc, v8, v29
	v_or_b32_e32 v8, 19, v9
	s_nop 0
	v_cndmask_b32_e32 v3, 0, v3, vcc
	v_cmp_le_i32_e32 vcc, v8, v29
	v_cvt_pk_bf16_f32 v1, v2, v3
	ds_write_b64 v10, v[0:1] offset:46080
	v_cvt_pk_bf16_f32 v0, v4, v5
	s_nop 0
	v_cndmask_b32_e32 v7, 0, v7, vcc
	v_cvt_pk_bf16_f32 v1, v6, v7
	ds_write_b64 v10, v[0:1] offset:46112
	s_waitcnt vmcnt(0)
	s_nop 0
	s_waitcnt lgkmcnt(0)
	s_barrier
	ds_read_b128 v[36:39], v24 offset:27648
	ds_read_b128 v[186:189], v19 offset:46080
	ds_read_b128 v[190:193], v19 offset:48384
	ds_read_b128 v[194:197], v19 offset:50688
	ds_read_b128 v[206:209], v19 offset:52992
	ds_read_b128 v[218:221], v24 offset:27712
	ds_read_b128 v[222:225], v19 offset:46144
	ds_read_b128 v[226:229], v19 offset:53056
	ds_read_b128 v[230:233], v19 offset:48448
	ds_read_b128 v[234:237], v19 offset:50752
	s_nop 6
	s_waitcnt lgkmcnt(6)
	v_mfma_f32_16x16x32_bf16 v[32:35], v[36:39], v[194:197], 0
	s_nop 0
	v_mfma_f32_16x16x32_bf16 v[4:7], v[36:39], v[186:189], 0
	v_mfma_f32_16x16x32_bf16 v[8:11], v[36:39], v[190:193], 0
	s_nop 0
	s_waitcnt lgkmcnt(5)
	v_mfma_f32_16x16x32_bf16 v[0:3], v[36:39], v[206:209], 0
	s_nop 1
	s_waitcnt lgkmcnt(3)
	v_mfma_f32_16x16x32_bf16 v[12:15], v[218:221], v[222:225], v[4:7]
	s_nop 4
	s_waitcnt lgkmcnt(1)
	v_mfma_f32_16x16x32_bf16 v[8:11], v[218:221], v[230:233], v[8:11]
	s_nop 0
	s_waitcnt vmcnt(0)
	s_nop 0
	s_waitcnt lgkmcnt(0)
	v_mfma_f32_16x16x32_bf16 v[4:7], v[218:221], v[234:237], v[32:35]
	s_barrier
	v_mfma_f32_16x16x32_bf16 v[0:3], v[218:221], v[226:229], v[0:3]
	s_cbranch_scc1 .LBB0_1285
	s_ashr_i32 s1, s0, 31
	s_lshl_b64 s[0:1], s[0:1], 19
	v_readlane_b32 s14, v254, 9
	v_readlane_b32 s15, v254, 10
	s_add_u32 s0, s14, s0
	s_addc_u32 s1, s15, s1
	s_lshl_b32 s13, s13, 14
	s_add_u32 s0, s0, s13
	v_ashrrev_i32_e32 v19, 31, v18
	s_addc_u32 s1, s1, 0
	v_lshlrev_b64 v[18:19], 7, v[18:19]
	v_lshl_add_u64 v[18:19], s[0:1], 0, v[18:19]
	v_lshlrev_b32_e32 v16, 1, v16
	v_lshl_add_u64 v[18:19], v[18:19], 0, v[16:17]
	global_load_dwordx4 v[22:25], v[18:19], off
	s_nop 0
	global_load_dwordx4 v[18:21], v[18:19], off offset:64
	v_mul_u32_u24_e32 v16, 0x90, v30
	s_mov_b32 s13, 0
	s_mov_b64 s[0:1], -1
